# same as before plus alternating k order inside accumulate chains so the B-fragment operand repeats across chain boundaries
# speedup vs baseline: 1.0622x; 1.0017x over previous
.LBB0_124:
	ds_read_b128 v[138:141], v151
	ds_read_b128 v[142:145], v151 offset:1024
	ds_read_b128 v[158:161], v151 offset:2048
	ds_read_b128 v[162:165], v151 offset:3072
	ds_read_b128 v[166:169], v152
	ds_read_b128 v[170:173], v152 offset:1024
	ds_read_b128 v[174:177], v152 offset:2048
	ds_read_b128 v[178:181], v152 offset:3072
	s_add_i32 s47, s9, s10
	s_add_i32 s75, s47, 0x100
	s_add_i32 s13, s9, s11
	s_cmp_eq_u32 s9, s12
	s_cselect_b32 s13, s7, s13
	s_cselect_b32 s80, s6, s75
	s_add_i32 s75, s47, 0x80
	s_mov_b32 m0, s58
	ds_read_b128 v[182:185], v153
	ds_read_b128 v[186:189], v153 offset:1024
	buffer_load_dwordx4 v1, s[28:31], s75 offen lds
	s_mov_b32 m0, s59
	ds_read_b128 v[190:193], v153 offset:2048
	ds_read_b128 v[194:197], v153 offset:3072
	buffer_load_dwordx4 v147, s[28:31], s75 offen lds
	s_add_i32 s47, s47, 0x80080
	s_mov_b32 m0, s70
	ds_read_b128 v[198:201], v153 offset:4096
	ds_read_b128 v[202:205], v153 offset:5120
	buffer_load_dwordx4 v1, s[28:31], s47 offen lds
	s_mov_b32 m0, s71
	ds_read_b128 v[206:209], v153 offset:6144
	ds_read_b128 v[210:213], v153 offset:7168
	buffer_load_dwordx4 v147, s[28:31], s47 offen lds
	s_waitcnt vmcnt(8)
	s_waitcnt lgkmcnt(0)
	s_barrier
	s_waitcnt lgkmcnt(0)
	v_mfma_f32_16x16x32_bf16 v[130:133], v[138:141], v[182:185], v[130:133]
	v_mfma_f32_16x16x32_bf16 v[130:133], v[142:145], v[186:189], v[130:133]
	v_mfma_f32_16x16x32_bf16 v[114:117], v[142:145], v[194:197], v[114:117]
	v_mfma_f32_16x16x32_bf16 v[114:117], v[138:141], v[190:193], v[114:117]
	v_mfma_f32_16x16x32_bf16 v[98:101], v[138:141], v[198:201], v[98:101]
	v_mfma_f32_16x16x32_bf16 v[98:101], v[142:145], v[202:205], v[98:101]
	v_mfma_f32_16x16x32_bf16 v[82:85], v[142:145], v[210:213], v[82:85]
	v_mfma_f32_16x16x32_bf16 v[82:85], v[138:141], v[206:209], v[82:85]
	v_mfma_f32_16x16x32_bf16 v[126:129], v[158:161], v[182:185], v[126:129]
	v_mfma_f32_16x16x32_bf16 v[126:129], v[162:165], v[186:189], v[126:129]
	v_mfma_f32_16x16x32_bf16 v[110:113], v[162:165], v[194:197], v[110:113]
	v_mfma_f32_16x16x32_bf16 v[110:113], v[158:161], v[190:193], v[110:113]
	v_mfma_f32_16x16x32_bf16 v[94:97], v[158:161], v[198:201], v[94:97]
	v_mfma_f32_16x16x32_bf16 v[94:97], v[162:165], v[202:205], v[94:97]
	v_mfma_f32_16x16x32_bf16 v[78:81], v[162:165], v[210:213], v[78:81]
	v_mfma_f32_16x16x32_bf16 v[78:81], v[158:161], v[206:209], v[78:81]
	v_mfma_f32_16x16x32_bf16 v[122:125], v[166:169], v[182:185], v[122:125]
	v_mfma_f32_16x16x32_bf16 v[122:125], v[170:173], v[186:189], v[122:125]
	v_mfma_f32_16x16x32_bf16 v[106:109], v[170:173], v[194:197], v[106:109]
	v_mfma_f32_16x16x32_bf16 v[106:109], v[166:169], v[190:193], v[106:109]
	v_mfma_f32_16x16x32_bf16 v[90:93], v[166:169], v[198:201], v[90:93]
	v_mfma_f32_16x16x32_bf16 v[90:93], v[170:173], v[202:205], v[90:93]
	v_mfma_f32_16x16x32_bf16 v[74:77], v[170:173], v[210:213], v[74:77]
	v_mfma_f32_16x16x32_bf16 v[74:77], v[166:169], v[206:209], v[74:77]
	v_mfma_f32_16x16x32_bf16 v[118:121], v[174:177], v[182:185], v[118:121]
	v_mfma_f32_16x16x32_bf16 v[118:121], v[178:181], v[186:189], v[118:121]
	v_mfma_f32_16x16x32_bf16 v[102:105], v[178:181], v[194:197], v[102:105]
	v_mfma_f32_16x16x32_bf16 v[102:105], v[174:177], v[190:193], v[102:105]
	v_mfma_f32_16x16x32_bf16 v[86:89], v[174:177], v[198:201], v[86:89]
	v_mfma_f32_16x16x32_bf16 v[86:89], v[178:181], v[202:205], v[86:89]
	v_mfma_f32_16x16x32_bf16 v[70:73], v[178:181], v[210:213], v[70:73]
	v_mfma_f32_16x16x32_bf16 v[70:73], v[174:177], v[206:209], v[70:73]
	s_barrier
	s_mov_b32 m0, s91
	s_mov_b32 s75, s31
	ds_read_b128 v[182:185], v153 offset:16384
	ds_read_b128 v[186:189], v153 offset:17408
	buffer_load_dwordx4 v146, s[72:75], s13 offen lds
	s_mov_b32 m0, s93
	ds_read_b128 v[190:193], v153 offset:18432
	ds_read_b128 v[194:197], v153 offset:19456
	buffer_load_dwordx4 v148, s[72:75], s13 offen lds
	s_add_i32 s47, s13, 0x80000
	s_mov_b32 m0, s95
	ds_read_b128 v[198:201], v153 offset:20480
	ds_read_b128 v[202:205], v153 offset:21504
	buffer_load_dwordx4 v146, s[72:75], s47 offen lds
	s_mov_b32 m0, s35
	ds_read_b128 v[206:209], v153 offset:22528
	ds_read_b128 v[210:213], v153 offset:23552
	buffer_load_dwordx4 v148, s[72:75], s47 offen lds
	s_waitcnt vmcnt(6)
	s_waitcnt lgkmcnt(0)
	s_barrier
	s_waitcnt lgkmcnt(0)
	v_mfma_f32_16x16x32_bf16 v[66:69], v[138:141], v[182:185], v[66:69]
	v_mfma_f32_16x16x32_bf16 v[66:69], v[142:145], v[186:189], v[66:69]
	v_mfma_f32_16x16x32_bf16 v[50:53], v[142:145], v[194:197], v[50:53]
	v_mfma_f32_16x16x32_bf16 v[50:53], v[138:141], v[190:193], v[50:53]
	v_mfma_f32_16x16x32_bf16 v[34:37], v[138:141], v[198:201], v[34:37]
	v_mfma_f32_16x16x32_bf16 v[34:37], v[142:145], v[202:205], v[34:37]
	v_mfma_f32_16x16x32_bf16 v[18:21], v[142:145], v[210:213], v[18:21]
	v_mfma_f32_16x16x32_bf16 v[18:21], v[138:141], v[206:209], v[18:21]
	v_mfma_f32_16x16x32_bf16 v[62:65], v[158:161], v[182:185], v[62:65]
	v_mfma_f32_16x16x32_bf16 v[62:65], v[162:165], v[186:189], v[62:65]
	v_mfma_f32_16x16x32_bf16 v[46:49], v[162:165], v[194:197], v[46:49]
	v_mfma_f32_16x16x32_bf16 v[46:49], v[158:161], v[190:193], v[46:49]
	v_mfma_f32_16x16x32_bf16 v[30:33], v[158:161], v[198:201], v[30:33]
	v_mfma_f32_16x16x32_bf16 v[30:33], v[162:165], v[202:205], v[30:33]
	v_mfma_f32_16x16x32_bf16 v[14:17], v[162:165], v[210:213], v[14:17]
	v_mfma_f32_16x16x32_bf16 v[14:17], v[158:161], v[206:209], v[14:17]
	v_mfma_f32_16x16x32_bf16 v[58:61], v[166:169], v[182:185], v[58:61]
	v_mfma_f32_16x16x32_bf16 v[58:61], v[170:173], v[186:189], v[58:61]
	v_mfma_f32_16x16x32_bf16 v[42:45], v[170:173], v[194:197], v[42:45]
	v_mfma_f32_16x16x32_bf16 v[42:45], v[166:169], v[190:193], v[42:45]
	v_mfma_f32_16x16x32_bf16 v[26:29], v[166:169], v[198:201], v[26:29]
	v_mfma_f32_16x16x32_bf16 v[26:29], v[170:173], v[202:205], v[26:29]
	v_mfma_f32_16x16x32_bf16 v[10:13], v[170:173], v[210:213], v[10:13]
	v_mfma_f32_16x16x32_bf16 v[10:13], v[166:169], v[206:209], v[10:13]
	v_mfma_f32_16x16x32_bf16 v[54:57], v[174:177], v[182:185], v[54:57]
	v_mfma_f32_16x16x32_bf16 v[54:57], v[178:181], v[186:189], v[54:57]
	v_mfma_f32_16x16x32_bf16 v[38:41], v[178:181], v[194:197], v[38:41]
	v_mfma_f32_16x16x32_bf16 v[38:41], v[174:177], v[190:193], v[38:41]
	v_mfma_f32_16x16x32_bf16 v[22:25], v[174:177], v[198:201], v[22:25]
	v_mfma_f32_16x16x32_bf16 v[22:25], v[178:181], v[202:205], v[22:25]
	v_mfma_f32_16x16x32_bf16 v[4:7], v[174:177], v[206:209], v[6:9]
	v_mfma_f32_16x16x32_bf16 v[4:7], v[178:181], v[210:213], v[4:7]
	s_barrier
	ds_read_b128 v[138:141], v154
	ds_read_b128 v[142:145], v154 offset:1024
	ds_read_b128 v[158:161], v154 offset:2048
	ds_read_b128 v[162:165], v154 offset:3072
	ds_read_b128 v[166:169], v155
	ds_read_b128 v[170:173], v155 offset:1024
	ds_read_b128 v[174:177], v155 offset:2048
	ds_read_b128 v[178:181], v155 offset:3072
	s_mov_b32 m0, s77
	ds_read_b128 v[182:185], v153 offset:32768
	ds_read_b128 v[186:189], v153 offset:33792
	buffer_load_dwordx4 v1, s[28:31], s80 offen lds
	s_mov_b32 m0, s84
	ds_read_b128 v[190:193], v153 offset:34816
	ds_read_b128 v[194:197], v153 offset:35840
	buffer_load_dwordx4 v147, s[28:31], s80 offen lds
	s_add_i32 s80, s80, 0x80000
	s_mov_b32 m0, s85
	ds_read_b128 v[198:201], v153 offset:36864
	ds_read_b128 v[202:205], v153 offset:37888
	buffer_load_dwordx4 v1, s[28:31], s80 offen lds
	s_mov_b32 m0, s48
	ds_read_b128 v[206:209], v153 offset:38912
	ds_read_b128 v[210:213], v153 offset:39936
	buffer_load_dwordx4 v147, s[28:31], s80 offen lds
	s_waitcnt vmcnt(8)
	s_waitcnt lgkmcnt(0)
	s_barrier
	s_waitcnt lgkmcnt(0)
	v_mfma_f32_16x16x32_bf16 v[130:133], v[138:141], v[182:185], v[130:133]
	v_mfma_f32_16x16x32_bf16 v[130:133], v[142:145], v[186:189], v[130:133]
	v_mfma_f32_16x16x32_bf16 v[114:117], v[142:145], v[194:197], v[114:117]
	v_mfma_f32_16x16x32_bf16 v[114:117], v[138:141], v[190:193], v[114:117]
	v_mfma_f32_16x16x32_bf16 v[98:101], v[138:141], v[198:201], v[98:101]
	v_mfma_f32_16x16x32_bf16 v[98:101], v[142:145], v[202:205], v[98:101]
	v_mfma_f32_16x16x32_bf16 v[82:85], v[142:145], v[210:213], v[82:85]
	v_mfma_f32_16x16x32_bf16 v[82:85], v[138:141], v[206:209], v[82:85]
	v_mfma_f32_16x16x32_bf16 v[126:129], v[158:161], v[182:185], v[126:129]
	v_mfma_f32_16x16x32_bf16 v[126:129], v[162:165], v[186:189], v[126:129]
	v_mfma_f32_16x16x32_bf16 v[110:113], v[162:165], v[194:197], v[110:113]
	v_mfma_f32_16x16x32_bf16 v[110:113], v[158:161], v[190:193], v[110:113]
	v_mfma_f32_16x16x32_bf16 v[94:97], v[158:161], v[198:201], v[94:97]
	v_mfma_f32_16x16x32_bf16 v[94:97], v[162:165], v[202:205], v[94:97]
	v_mfma_f32_16x16x32_bf16 v[78:81], v[162:165], v[210:213], v[78:81]
	v_mfma_f32_16x16x32_bf16 v[78:81], v[158:161], v[206:209], v[78:81]
	v_mfma_f32_16x16x32_bf16 v[122:125], v[166:169], v[182:185], v[122:125]
	v_mfma_f32_16x16x32_bf16 v[122:125], v[170:173], v[186:189], v[122:125]
	v_mfma_f32_16x16x32_bf16 v[106:109], v[170:173], v[194:197], v[106:109]
	v_mfma_f32_16x16x32_bf16 v[106:109], v[166:169], v[190:193], v[106:109]
	v_mfma_f32_16x16x32_bf16 v[90:93], v[166:169], v[198:201], v[90:93]
	v_mfma_f32_16x16x32_bf16 v[90:93], v[170:173], v[202:205], v[90:93]
	v_mfma_f32_16x16x32_bf16 v[74:77], v[170:173], v[210:213], v[74:77]
	v_mfma_f32_16x16x32_bf16 v[74:77], v[166:169], v[206:209], v[74:77]
	v_mfma_f32_16x16x32_bf16 v[118:121], v[174:177], v[182:185], v[118:121]
	v_mfma_f32_16x16x32_bf16 v[118:121], v[178:181], v[186:189], v[118:121]
	v_mfma_f32_16x16x32_bf16 v[102:105], v[178:181], v[194:197], v[102:105]
	v_mfma_f32_16x16x32_bf16 v[102:105], v[174:177], v[190:193], v[102:105]
	v_mfma_f32_16x16x32_bf16 v[86:89], v[174:177], v[198:201], v[86:89]
	v_mfma_f32_16x16x32_bf16 v[86:89], v[178:181], v[202:205], v[86:89]
	v_mfma_f32_16x16x32_bf16 v[70:73], v[178:181], v[210:213], v[70:73]
	v_mfma_f32_16x16x32_bf16 v[70:73], v[174:177], v[206:209], v[70:73]
	s_barrier
	s_mov_b32 m0, s78
	s_add_i32 s47, s13, 0x80
	ds_read_b128 v[182:185], v153 offset:49152
	ds_read_b128 v[186:189], v153 offset:50176
	buffer_load_dwordx4 v146, s[72:75], s47 offen lds
	s_mov_b32 m0, s79
	ds_read_b128 v[190:193], v153 offset:51200
	ds_read_b128 v[194:197], v153 offset:52224
	buffer_load_dwordx4 v148, s[72:75], s47 offen lds
	s_add_i32 s13, s13, 0x80080
	s_mov_b32 m0, s86
	ds_read_b128 v[198:201], v153 offset:53248
	ds_read_b128 v[202:205], v153 offset:54272
	buffer_load_dwordx4 v146, s[72:75], s13 offen lds
	s_mov_b32 m0, s87
	ds_read_b128 v[206:209], v153 offset:55296
	ds_read_b128 v[210:213], v153 offset:56320
	buffer_load_dwordx4 v148, s[72:75], s13 offen lds
	s_waitcnt vmcnt(6)
	s_waitcnt lgkmcnt(0)
	s_barrier
	s_waitcnt lgkmcnt(0)
	v_mfma_f32_16x16x32_bf16 v[66:69], v[138:141], v[182:185], v[66:69]
	v_mfma_f32_16x16x32_bf16 v[66:69], v[142:145], v[186:189], v[66:69]
	v_mfma_f32_16x16x32_bf16 v[50:53], v[142:145], v[194:197], v[50:53]
	v_mfma_f32_16x16x32_bf16 v[50:53], v[138:141], v[190:193], v[50:53]
	v_mfma_f32_16x16x32_bf16 v[34:37], v[138:141], v[198:201], v[34:37]
	v_mfma_f32_16x16x32_bf16 v[34:37], v[142:145], v[202:205], v[34:37]
	v_mfma_f32_16x16x32_bf16 v[18:21], v[142:145], v[210:213], v[18:21]
	v_mfma_f32_16x16x32_bf16 v[18:21], v[138:141], v[206:209], v[18:21]
	v_mfma_f32_16x16x32_bf16 v[62:65], v[158:161], v[182:185], v[62:65]
	v_mfma_f32_16x16x32_bf16 v[62:65], v[162:165], v[186:189], v[62:65]
	v_mfma_f32_16x16x32_bf16 v[46:49], v[162:165], v[194:197], v[46:49]
	v_mfma_f32_16x16x32_bf16 v[46:49], v[158:161], v[190:193], v[46:49]
	v_mfma_f32_16x16x32_bf16 v[30:33], v[158:161], v[198:201], v[30:33]
	v_mfma_f32_16x16x32_bf16 v[30:33], v[162:165], v[202:205], v[30:33]
	v_mfma_f32_16x16x32_bf16 v[14:17], v[162:165], v[210:213], v[14:17]
	v_mfma_f32_16x16x32_bf16 v[14:17], v[158:161], v[206:209], v[14:17]
	v_mfma_f32_16x16x32_bf16 v[58:61], v[166:169], v[182:185], v[58:61]
	v_mfma_f32_16x16x32_bf16 v[58:61], v[170:173], v[186:189], v[58:61]
	v_mfma_f32_16x16x32_bf16 v[42:45], v[170:173], v[194:197], v[42:45]
	v_mfma_f32_16x16x32_bf16 v[42:45], v[166:169], v[190:193], v[42:45]
	v_mfma_f32_16x16x32_bf16 v[26:29], v[166:169], v[198:201], v[26:29]
	v_mfma_f32_16x16x32_bf16 v[26:29], v[170:173], v[202:205], v[26:29]
	v_mfma_f32_16x16x32_bf16 v[8:11], v[166:169], v[206:209], v[10:13]
	v_mfma_f32_16x16x32_bf16 v[10:13], v[170:173], v[210:213], v[8:11]
	v_mfma_f32_16x16x32_bf16 v[54:57], v[174:177], v[182:185], v[54:57]
	v_mfma_f32_16x16x32_bf16 v[54:57], v[178:181], v[186:189], v[54:57]
	v_mfma_f32_16x16x32_bf16 v[38:41], v[178:181], v[194:197], v[38:41]
	v_mfma_f32_16x16x32_bf16 v[38:41], v[174:177], v[190:193], v[38:41]
	v_mfma_f32_16x16x32_bf16 v[22:25], v[174:177], v[198:201], v[22:25]
	v_mfma_f32_16x16x32_bf16 v[22:25], v[178:181], v[202:205], v[22:25]
	v_mfma_f32_16x16x32_bf16 v[4:7], v[174:177], v[206:209], v[4:7]
	v_mfma_f32_16x16x32_bf16 v[6:9], v[178:181], v[210:213], v[4:7]
	s_barrier
	s_add_i32 s8, s8, 2
	s_addk_i32 s10, 0x100
	s_addk_i32 s11, 0x100
	s_addk_i32 s12, 0xff00
	s_cmp_gt_u32 s8, 29
	s_cbranch_scc0 .LBB0_124
	v_readlane_b32 s6, v254, 26
	v_readlane_b32 s7, v254, 27
	s_and_b64 vcc, exec, s[6:7]
	s_cbranch_vccz .LBB0_127
	s_barrier

.LBB0_528:
	v_add_u32_e32 v3, 0x10000, v171
	ds_read_b128 v[134:137], v3
	ds_read_b128 v[138:141], v3 offset:1024
	ds_read_b128 v[142:145], v3 offset:2048
	ds_read_b128 v[146:149], v3 offset:3072
	v_add_u32_e32 v3, 0x14000, v171
	ds_read_b128 v[150:153], v3
	ds_read_b128 v[154:157], v3 offset:1024
	ds_read_b128 v[174:177], v3 offset:2048
	ds_read_b128 v[178:181], v3 offset:3072
	s_add_i32 s71, s63, s94
	s_add_i32 s97, s71, 0x100
	s_add_i32 s96, s63, s95
	s_cmp_eq_u32 s63, s93
	s_cselect_b32 s96, s90, s96
	s_cselect_b32 s97, s89, s97
	s_add_i32 vcc_lo, s71, 0x80
	s_mov_b32 m0, s79
	ds_read_b128 v[182:185], v172
	ds_read_b128 v[186:189], v172 offset:1024
	buffer_load_dwordx4 v1, s[48:51], vcc_lo offen lds
	s_mov_b32 m0, s80
	ds_read_b128 v[190:193], v172 offset:2048
	ds_read_b128 v[194:197], v172 offset:3072
	buffer_load_dwordx4 v167, s[48:51], vcc_lo offen lds
	s_add_i32 s71, s71, 0xc0080
	s_mov_b32 m0, s81
	ds_read_b128 v[198:201], v172 offset:4096
	ds_read_b128 v[202:205], v172 offset:5120
	buffer_load_dwordx4 v1, s[48:51], s71 offen lds
	s_mov_b32 m0, s82
	ds_read_b128 v[206:209], v172 offset:6144
	ds_read_b128 v[210:213], v172 offset:7168
	buffer_load_dwordx4 v167, s[48:51], s71 offen lds
	s_waitcnt vmcnt(8)
	s_waitcnt lgkmcnt(0)
	s_barrier
	s_waitcnt lgkmcnt(0)
	v_mfma_f32_16x16x32_bf16 v[130:133], v[134:137], v[182:185], v[130:133]
	v_mfma_f32_16x16x32_bf16 v[130:133], v[138:141], v[186:189], v[130:133]
	v_mfma_f32_16x16x32_bf16 v[114:117], v[138:141], v[194:197], v[114:117]
	v_mfma_f32_16x16x32_bf16 v[114:117], v[134:137], v[190:193], v[114:117]
	v_mfma_f32_16x16x32_bf16 v[98:101], v[134:137], v[198:201], v[98:101]
	v_mfma_f32_16x16x32_bf16 v[98:101], v[138:141], v[202:205], v[98:101]
	v_mfma_f32_16x16x32_bf16 v[82:85], v[138:141], v[210:213], v[82:85]
	v_mfma_f32_16x16x32_bf16 v[82:85], v[134:137], v[206:209], v[82:85]
	v_mfma_f32_16x16x32_bf16 v[126:129], v[142:145], v[182:185], v[126:129]
	v_mfma_f32_16x16x32_bf16 v[126:129], v[146:149], v[186:189], v[126:129]
	v_mfma_f32_16x16x32_bf16 v[110:113], v[146:149], v[194:197], v[110:113]
	v_mfma_f32_16x16x32_bf16 v[110:113], v[142:145], v[190:193], v[110:113]
	v_mfma_f32_16x16x32_bf16 v[94:97], v[142:145], v[198:201], v[94:97]
	v_mfma_f32_16x16x32_bf16 v[94:97], v[146:149], v[202:205], v[94:97]
	v_mfma_f32_16x16x32_bf16 v[78:81], v[146:149], v[210:213], v[78:81]
	v_mfma_f32_16x16x32_bf16 v[78:81], v[142:145], v[206:209], v[78:81]
	v_mfma_f32_16x16x32_bf16 v[122:125], v[150:153], v[182:185], v[122:125]
	v_mfma_f32_16x16x32_bf16 v[122:125], v[154:157], v[186:189], v[122:125]
	v_mfma_f32_16x16x32_bf16 v[106:109], v[154:157], v[194:197], v[106:109]
	v_mfma_f32_16x16x32_bf16 v[106:109], v[150:153], v[190:193], v[106:109]
	v_mfma_f32_16x16x32_bf16 v[90:93], v[150:153], v[198:201], v[90:93]
	v_mfma_f32_16x16x32_bf16 v[90:93], v[154:157], v[202:205], v[90:93]
	v_mfma_f32_16x16x32_bf16 v[74:77], v[154:157], v[210:213], v[74:77]
	v_mfma_f32_16x16x32_bf16 v[74:77], v[150:153], v[206:209], v[74:77]
	v_mfma_f32_16x16x32_bf16 v[118:121], v[174:177], v[182:185], v[118:121]
	v_mfma_f32_16x16x32_bf16 v[118:121], v[178:181], v[186:189], v[118:121]
	v_mfma_f32_16x16x32_bf16 v[102:105], v[178:181], v[194:197], v[102:105]
	v_mfma_f32_16x16x32_bf16 v[102:105], v[174:177], v[190:193], v[102:105]
	v_mfma_f32_16x16x32_bf16 v[86:89], v[174:177], v[198:201], v[86:89]
	v_mfma_f32_16x16x32_bf16 v[86:89], v[178:181], v[202:205], v[86:89]
	v_mfma_f32_16x16x32_bf16 v[70:73], v[178:181], v[210:213], v[70:73]
	v_mfma_f32_16x16x32_bf16 v[70:73], v[174:177], v[206:209], v[70:73]
	s_barrier
	s_mov_b32 m0, s35
	s_mov_b32 s71, s51
	ds_read_b128 v[182:185], v172 offset:16384
	ds_read_b128 v[186:189], v172 offset:17408
	buffer_load_dwordx4 v166, s[68:71], s96 offen lds
	s_mov_b32 m0, s45
	ds_read_b128 v[190:193], v172 offset:18432
	ds_read_b128 v[194:197], v172 offset:19456
	buffer_load_dwordx4 v168, s[68:71], s96 offen lds
	s_add_i32 vcc_lo, s96, 0xc0000
	s_mov_b32 m0, s64
	ds_read_b128 v[198:201], v172 offset:20480
	ds_read_b128 v[202:205], v172 offset:21504
	buffer_load_dwordx4 v166, s[68:71], vcc_lo offen lds
	s_mov_b32 m0, s65
	ds_read_b128 v[206:209], v172 offset:22528
	ds_read_b128 v[210:213], v172 offset:23552
	buffer_load_dwordx4 v168, s[68:71], vcc_lo offen lds
	s_waitcnt vmcnt(6)
	s_waitcnt lgkmcnt(0)
	s_barrier
	s_waitcnt lgkmcnt(0)
	v_mfma_f32_16x16x32_bf16 v[66:69], v[134:137], v[182:185], v[66:69]
	v_mfma_f32_16x16x32_bf16 v[66:69], v[138:141], v[186:189], v[66:69]
	v_mfma_f32_16x16x32_bf16 v[50:53], v[138:141], v[194:197], v[50:53]
	v_mfma_f32_16x16x32_bf16 v[50:53], v[134:137], v[190:193], v[50:53]
	v_mfma_f32_16x16x32_bf16 v[34:37], v[134:137], v[198:201], v[34:37]
	v_mfma_f32_16x16x32_bf16 v[34:37], v[138:141], v[202:205], v[34:37]
	v_mfma_f32_16x16x32_bf16 v[18:21], v[138:141], v[210:213], v[18:21]
	v_mfma_f32_16x16x32_bf16 v[18:21], v[134:137], v[206:209], v[18:21]
	v_mfma_f32_16x16x32_bf16 v[62:65], v[142:145], v[182:185], v[62:65]
	v_mfma_f32_16x16x32_bf16 v[62:65], v[146:149], v[186:189], v[62:65]
	v_mfma_f32_16x16x32_bf16 v[46:49], v[146:149], v[194:197], v[46:49]
	v_mfma_f32_16x16x32_bf16 v[46:49], v[142:145], v[190:193], v[46:49]
	v_mfma_f32_16x16x32_bf16 v[30:33], v[142:145], v[198:201], v[30:33]
	v_mfma_f32_16x16x32_bf16 v[30:33], v[146:149], v[202:205], v[30:33]
	v_mfma_f32_16x16x32_bf16 v[14:17], v[146:149], v[210:213], v[14:17]
	v_mfma_f32_16x16x32_bf16 v[14:17], v[142:145], v[206:209], v[14:17]
	v_mfma_f32_16x16x32_bf16 v[58:61], v[150:153], v[182:185], v[58:61]
	v_mfma_f32_16x16x32_bf16 v[58:61], v[154:157], v[186:189], v[58:61]
	v_mfma_f32_16x16x32_bf16 v[42:45], v[154:157], v[194:197], v[42:45]
	v_mfma_f32_16x16x32_bf16 v[42:45], v[150:153], v[190:193], v[42:45]
	v_mfma_f32_16x16x32_bf16 v[26:29], v[150:153], v[198:201], v[26:29]
	v_mfma_f32_16x16x32_bf16 v[26:29], v[154:157], v[202:205], v[26:29]
	v_mfma_f32_16x16x32_bf16 v[10:13], v[154:157], v[210:213], v[10:13]
	v_mfma_f32_16x16x32_bf16 v[10:13], v[150:153], v[206:209], v[10:13]
	v_mfma_f32_16x16x32_bf16 v[54:57], v[174:177], v[182:185], v[54:57]
	v_mfma_f32_16x16x32_bf16 v[54:57], v[178:181], v[186:189], v[54:57]
	v_mfma_f32_16x16x32_bf16 v[38:41], v[178:181], v[194:197], v[38:41]
	v_mfma_f32_16x16x32_bf16 v[38:41], v[174:177], v[190:193], v[38:41]
	v_mfma_f32_16x16x32_bf16 v[22:25], v[174:177], v[198:201], v[22:25]
	v_mfma_f32_16x16x32_bf16 v[22:25], v[178:181], v[202:205], v[22:25]
	v_mfma_f32_16x16x32_bf16 v[4:7], v[174:177], v[206:209], v[6:9]
	v_mfma_f32_16x16x32_bf16 v[4:7], v[178:181], v[210:213], v[4:7]
	s_barrier
	v_add_u32_e32 v3, 0x18000, v171
	ds_read_b128 v[134:137], v3
	ds_read_b128 v[138:141], v3 offset:1024
	ds_read_b128 v[142:145], v3 offset:2048
	ds_read_b128 v[146:149], v3 offset:3072
	v_add_u32_e32 v3, 0x1c000, v171
	ds_read_b128 v[150:153], v3
	ds_read_b128 v[154:157], v3 offset:1024
	ds_read_b128 v[174:177], v3 offset:2048
	ds_read_b128 v[178:181], v3 offset:3072
	s_mov_b32 m0, s29
	ds_read_b128 v[182:185], v172 offset:32768
	ds_read_b128 v[186:189], v172 offset:33792
	buffer_load_dwordx4 v1, s[48:51], s97 offen lds
	s_mov_b32 m0, s66
	ds_read_b128 v[190:193], v172 offset:34816
	ds_read_b128 v[194:197], v172 offset:35840
	buffer_load_dwordx4 v167, s[48:51], s97 offen lds
	s_add_i32 s97, s97, 0xc0000
	s_mov_b32 m0, s67
	ds_read_b128 v[198:201], v172 offset:36864
	ds_read_b128 v[202:205], v172 offset:37888
	buffer_load_dwordx4 v1, s[48:51], s97 offen lds
	s_mov_b32 m0, s72
	ds_read_b128 v[206:209], v172 offset:38912
	ds_read_b128 v[210:213], v172 offset:39936
	buffer_load_dwordx4 v167, s[48:51], s97 offen lds
	s_waitcnt vmcnt(8)
	s_waitcnt lgkmcnt(0)
	s_barrier
	s_waitcnt lgkmcnt(0)
	v_mfma_f32_16x16x32_bf16 v[130:133], v[134:137], v[182:185], v[130:133]
	v_mfma_f32_16x16x32_bf16 v[130:133], v[138:141], v[186:189], v[130:133]
	v_mfma_f32_16x16x32_bf16 v[114:117], v[138:141], v[194:197], v[114:117]
	v_mfma_f32_16x16x32_bf16 v[114:117], v[134:137], v[190:193], v[114:117]
	v_mfma_f32_16x16x32_bf16 v[98:101], v[134:137], v[198:201], v[98:101]
	v_mfma_f32_16x16x32_bf16 v[98:101], v[138:141], v[202:205], v[98:101]
	v_mfma_f32_16x16x32_bf16 v[82:85], v[138:141], v[210:213], v[82:85]
	v_mfma_f32_16x16x32_bf16 v[82:85], v[134:137], v[206:209], v[82:85]
	v_mfma_f32_16x16x32_bf16 v[126:129], v[142:145], v[182:185], v[126:129]
	v_mfma_f32_16x16x32_bf16 v[126:129], v[146:149], v[186:189], v[126:129]
	v_mfma_f32_16x16x32_bf16 v[110:113], v[146:149], v[194:197], v[110:113]
	v_mfma_f32_16x16x32_bf16 v[110:113], v[142:145], v[190:193], v[110:113]
	v_mfma_f32_16x16x32_bf16 v[94:97], v[142:145], v[198:201], v[94:97]
	v_mfma_f32_16x16x32_bf16 v[94:97], v[146:149], v[202:205], v[94:97]
	v_mfma_f32_16x16x32_bf16 v[78:81], v[146:149], v[210:213], v[78:81]
	v_mfma_f32_16x16x32_bf16 v[78:81], v[142:145], v[206:209], v[78:81]
	v_mfma_f32_16x16x32_bf16 v[122:125], v[150:153], v[182:185], v[122:125]
	v_mfma_f32_16x16x32_bf16 v[122:125], v[154:157], v[186:189], v[122:125]
	v_mfma_f32_16x16x32_bf16 v[106:109], v[154:157], v[194:197], v[106:109]
	v_mfma_f32_16x16x32_bf16 v[106:109], v[150:153], v[190:193], v[106:109]
	v_mfma_f32_16x16x32_bf16 v[90:93], v[150:153], v[198:201], v[90:93]
	v_mfma_f32_16x16x32_bf16 v[90:93], v[154:157], v[202:205], v[90:93]
	v_mfma_f32_16x16x32_bf16 v[74:77], v[154:157], v[210:213], v[74:77]
	v_mfma_f32_16x16x32_bf16 v[74:77], v[150:153], v[206:209], v[74:77]
	v_mfma_f32_16x16x32_bf16 v[118:121], v[174:177], v[182:185], v[118:121]
	v_mfma_f32_16x16x32_bf16 v[118:121], v[178:181], v[186:189], v[118:121]
	v_mfma_f32_16x16x32_bf16 v[102:105], v[178:181], v[194:197], v[102:105]
	v_mfma_f32_16x16x32_bf16 v[102:105], v[174:177], v[190:193], v[102:105]
	v_mfma_f32_16x16x32_bf16 v[86:89], v[174:177], v[198:201], v[86:89]
	v_mfma_f32_16x16x32_bf16 v[86:89], v[178:181], v[202:205], v[86:89]
	v_mfma_f32_16x16x32_bf16 v[70:73], v[178:181], v[210:213], v[70:73]
	v_mfma_f32_16x16x32_bf16 v[70:73], v[174:177], v[206:209], v[70:73]
	s_barrier
	s_mov_b32 m0, s74
	s_add_i32 s97, s96, 0x80
	ds_read_b128 v[182:185], v172 offset:49152
	ds_read_b128 v[186:189], v172 offset:50176
	buffer_load_dwordx4 v166, s[68:71], s97 offen lds
	s_mov_b32 m0, s75
	ds_read_b128 v[190:193], v172 offset:51200
	ds_read_b128 v[194:197], v172 offset:52224
	buffer_load_dwordx4 v168, s[68:71], s97 offen lds
	s_add_i32 s96, s96, 0xc0080
	s_mov_b32 m0, s77
	ds_read_b128 v[198:201], v172 offset:53248
	ds_read_b128 v[202:205], v172 offset:54272
	buffer_load_dwordx4 v166, s[68:71], s96 offen lds
	s_mov_b32 m0, s78
	ds_read_b128 v[206:209], v172 offset:55296
	ds_read_b128 v[210:213], v172 offset:56320
	buffer_load_dwordx4 v168, s[68:71], s96 offen lds
	s_waitcnt vmcnt(6)
	s_waitcnt lgkmcnt(0)
	s_barrier
	s_waitcnt lgkmcnt(0)
	v_mfma_f32_16x16x32_bf16 v[66:69], v[134:137], v[182:185], v[66:69]
	v_mfma_f32_16x16x32_bf16 v[66:69], v[138:141], v[186:189], v[66:69]
	v_mfma_f32_16x16x32_bf16 v[50:53], v[138:141], v[194:197], v[50:53]
	v_mfma_f32_16x16x32_bf16 v[50:53], v[134:137], v[190:193], v[50:53]
	v_mfma_f32_16x16x32_bf16 v[34:37], v[134:137], v[198:201], v[34:37]
	v_mfma_f32_16x16x32_bf16 v[34:37], v[138:141], v[202:205], v[34:37]
	v_mfma_f32_16x16x32_bf16 v[18:21], v[138:141], v[210:213], v[18:21]
	v_mfma_f32_16x16x32_bf16 v[18:21], v[134:137], v[206:209], v[18:21]
	v_mfma_f32_16x16x32_bf16 v[62:65], v[142:145], v[182:185], v[62:65]
	v_mfma_f32_16x16x32_bf16 v[62:65], v[146:149], v[186:189], v[62:65]
	v_mfma_f32_16x16x32_bf16 v[46:49], v[146:149], v[194:197], v[46:49]
	v_mfma_f32_16x16x32_bf16 v[46:49], v[142:145], v[190:193], v[46:49]
	v_mfma_f32_16x16x32_bf16 v[30:33], v[142:145], v[198:201], v[30:33]
	v_mfma_f32_16x16x32_bf16 v[30:33], v[146:149], v[202:205], v[30:33]
	v_mfma_f32_16x16x32_bf16 v[14:17], v[146:149], v[210:213], v[14:17]
	v_mfma_f32_16x16x32_bf16 v[14:17], v[142:145], v[206:209], v[14:17]
	v_mfma_f32_16x16x32_bf16 v[58:61], v[150:153], v[182:185], v[58:61]
	v_mfma_f32_16x16x32_bf16 v[58:61], v[154:157], v[186:189], v[58:61]
	v_mfma_f32_16x16x32_bf16 v[42:45], v[154:157], v[194:197], v[42:45]
	v_mfma_f32_16x16x32_bf16 v[42:45], v[150:153], v[190:193], v[42:45]
	v_mfma_f32_16x16x32_bf16 v[26:29], v[150:153], v[198:201], v[26:29]
	v_mfma_f32_16x16x32_bf16 v[26:29], v[154:157], v[202:205], v[26:29]
	v_mfma_f32_16x16x32_bf16 v[8:11], v[150:153], v[206:209], v[10:13]
	v_mfma_f32_16x16x32_bf16 v[10:13], v[154:157], v[210:213], v[8:11]
	v_mfma_f32_16x16x32_bf16 v[54:57], v[174:177], v[182:185], v[54:57]
	v_mfma_f32_16x16x32_bf16 v[54:57], v[178:181], v[186:189], v[54:57]
	v_mfma_f32_16x16x32_bf16 v[38:41], v[178:181], v[194:197], v[38:41]
	v_mfma_f32_16x16x32_bf16 v[38:41], v[174:177], v[190:193], v[38:41]
	v_mfma_f32_16x16x32_bf16 v[22:25], v[174:177], v[198:201], v[22:25]
	v_mfma_f32_16x16x32_bf16 v[22:25], v[178:181], v[202:205], v[22:25]
	v_mfma_f32_16x16x32_bf16 v[4:7], v[174:177], v[206:209], v[4:7]
	v_mfma_f32_16x16x32_bf16 v[6:9], v[178:181], v[210:213], v[4:7]
	s_barrier
	s_add_i32 s92, s92, 2
	s_addk_i32 s95, 0x100
	s_addk_i32 s94, 0x100
	s_addk_i32 s93, 0xff00
	s_cmp_ge_u32 s92, s62
	s_cbranch_scc0 .LBB0_528
	s_branch .LBB0_523

.LBB0_605:
	v_add_u32_e32 v141, 0x10000, v139
	ds_read_b128 v[142:145], v141
	ds_read_b128 v[146:149], v141 offset:1024
	ds_read_b128 v[154:157], v141 offset:2048
	ds_read_b128 v[158:161], v141 offset:3072
	v_add_u32_e32 v141, 0x14000, v139
	ds_read_b128 v[162:165], v141
	ds_read_b128 v[166:169], v141 offset:1024
	ds_read_b128 v[170:173], v141 offset:2048
	ds_read_b128 v[174:177], v141 offset:3072
	s_add_i32 s47, s64, s82
	s_add_i32 s84, s47, 0x100
	s_add_i32 s83, s11, s82
	s_cmpk_eq_i32 s82, 0xf00
	s_cselect_b32 s83, s80, s83
	s_cselect_b32 s84, s79, s84
	s_add_i32 s85, s47, 0x80
	s_mov_b32 m0, s71
	ds_read_b128 v[178:181], v140
	ds_read_b128 v[182:185], v140 offset:1024
	buffer_load_dwordx4 v135, s[12:15], s85 offen lds
	s_mov_b32 m0, s72
	ds_read_b128 v[186:189], v140 offset:2048
	ds_read_b128 v[190:193], v140 offset:3072
	buffer_load_dwordx4 v137, s[12:15], s85 offen lds
	s_add_i32 s47, s47, 0x80080
	s_mov_b32 m0, s73
	ds_read_b128 v[194:197], v140 offset:4096
	ds_read_b128 v[198:201], v140 offset:5120
	buffer_load_dwordx4 v135, s[12:15], s47 offen lds
	s_mov_b32 m0, s74
	ds_read_b128 v[202:205], v140 offset:6144
	ds_read_b128 v[206:209], v140 offset:7168
	buffer_load_dwordx4 v137, s[12:15], s47 offen lds
	s_waitcnt vmcnt(8)
	s_waitcnt lgkmcnt(0)
	s_barrier
	s_waitcnt lgkmcnt(0)
	v_mfma_f32_16x16x32_bf16 v[126:129], v[142:145], v[178:181], v[126:129]
	v_mfma_f32_16x16x32_bf16 v[126:129], v[146:149], v[182:185], v[126:129]
	v_mfma_f32_16x16x32_bf16 v[110:113], v[146:149], v[190:193], v[110:113]
	v_mfma_f32_16x16x32_bf16 v[110:113], v[142:145], v[186:189], v[110:113]
	v_mfma_f32_16x16x32_bf16 v[94:97], v[142:145], v[194:197], v[94:97]
	v_mfma_f32_16x16x32_bf16 v[94:97], v[146:149], v[198:201], v[94:97]
	v_mfma_f32_16x16x32_bf16 v[78:81], v[146:149], v[206:209], v[78:81]
	v_mfma_f32_16x16x32_bf16 v[78:81], v[142:145], v[202:205], v[78:81]
	v_mfma_f32_16x16x32_bf16 v[122:125], v[154:157], v[178:181], v[122:125]
	v_mfma_f32_16x16x32_bf16 v[122:125], v[158:161], v[182:185], v[122:125]
	v_mfma_f32_16x16x32_bf16 v[106:109], v[158:161], v[190:193], v[106:109]
	v_mfma_f32_16x16x32_bf16 v[106:109], v[154:157], v[186:189], v[106:109]
	v_mfma_f32_16x16x32_bf16 v[90:93], v[154:157], v[194:197], v[90:93]
	v_mfma_f32_16x16x32_bf16 v[90:93], v[158:161], v[198:201], v[90:93]
	v_mfma_f32_16x16x32_bf16 v[74:77], v[158:161], v[206:209], v[74:77]
	v_mfma_f32_16x16x32_bf16 v[74:77], v[154:157], v[202:205], v[74:77]
	v_mfma_f32_16x16x32_bf16 v[118:121], v[162:165], v[178:181], v[118:121]
	v_mfma_f32_16x16x32_bf16 v[118:121], v[166:169], v[182:185], v[118:121]
	v_mfma_f32_16x16x32_bf16 v[102:105], v[166:169], v[190:193], v[102:105]
	v_mfma_f32_16x16x32_bf16 v[102:105], v[162:165], v[186:189], v[102:105]
	v_mfma_f32_16x16x32_bf16 v[86:89], v[162:165], v[194:197], v[86:89]
	v_mfma_f32_16x16x32_bf16 v[86:89], v[166:169], v[198:201], v[86:89]
	v_mfma_f32_16x16x32_bf16 v[70:73], v[166:169], v[206:209], v[70:73]
	v_mfma_f32_16x16x32_bf16 v[70:73], v[162:165], v[202:205], v[70:73]
	v_mfma_f32_16x16x32_bf16 v[114:117], v[170:173], v[178:181], v[114:117]
	v_mfma_f32_16x16x32_bf16 v[114:117], v[174:177], v[182:185], v[114:117]
	v_mfma_f32_16x16x32_bf16 v[98:101], v[174:177], v[190:193], v[98:101]
	v_mfma_f32_16x16x32_bf16 v[98:101], v[170:173], v[186:189], v[98:101]
	v_mfma_f32_16x16x32_bf16 v[82:85], v[170:173], v[194:197], v[82:85]
	v_mfma_f32_16x16x32_bf16 v[82:85], v[174:177], v[198:201], v[82:85]
	v_mfma_f32_16x16x32_bf16 v[66:69], v[174:177], v[206:209], v[66:69]
	v_mfma_f32_16x16x32_bf16 v[66:69], v[170:173], v[202:205], v[66:69]
	s_barrier
	s_mov_b32 m0, s58
	s_mov_b32 s47, s15
	ds_read_b128 v[178:181], v140 offset:16384
	ds_read_b128 v[182:185], v140 offset:17408
	buffer_load_dwordx4 v136, s[44:47], s83 offen lds
	s_mov_b32 m0, s60
	ds_read_b128 v[186:189], v140 offset:18432
	ds_read_b128 v[190:193], v140 offset:19456
	buffer_load_dwordx4 v138, s[44:47], s83 offen lds
	s_add_i32 s85, s83, 0x80000
	s_mov_b32 m0, s61
	ds_read_b128 v[194:197], v140 offset:20480
	ds_read_b128 v[198:201], v140 offset:21504
	buffer_load_dwordx4 v136, s[44:47], s85 offen lds
	s_mov_b32 m0, s62
	ds_read_b128 v[202:205], v140 offset:22528
	ds_read_b128 v[206:209], v140 offset:23552
	buffer_load_dwordx4 v138, s[44:47], s85 offen lds
	s_waitcnt vmcnt(6)
	s_waitcnt lgkmcnt(0)
	s_barrier
	s_waitcnt lgkmcnt(0)
	v_mfma_f32_16x16x32_bf16 v[62:65], v[142:145], v[178:181], v[62:65]
	v_mfma_f32_16x16x32_bf16 v[62:65], v[146:149], v[182:185], v[62:65]
	v_mfma_f32_16x16x32_bf16 v[46:49], v[146:149], v[190:193], v[46:49]
	v_mfma_f32_16x16x32_bf16 v[46:49], v[142:145], v[186:189], v[46:49]
	v_mfma_f32_16x16x32_bf16 v[30:33], v[142:145], v[194:197], v[30:33]
	v_mfma_f32_16x16x32_bf16 v[30:33], v[146:149], v[198:201], v[30:33]
	v_mfma_f32_16x16x32_bf16 v[14:17], v[146:149], v[206:209], v[14:17]
	v_mfma_f32_16x16x32_bf16 v[14:17], v[142:145], v[202:205], v[14:17]
	v_mfma_f32_16x16x32_bf16 v[58:61], v[154:157], v[178:181], v[58:61]
	v_mfma_f32_16x16x32_bf16 v[58:61], v[158:161], v[182:185], v[58:61]
	v_mfma_f32_16x16x32_bf16 v[42:45], v[158:161], v[190:193], v[42:45]
	v_mfma_f32_16x16x32_bf16 v[42:45], v[154:157], v[186:189], v[42:45]
	v_mfma_f32_16x16x32_bf16 v[26:29], v[154:157], v[194:197], v[26:29]
	v_mfma_f32_16x16x32_bf16 v[26:29], v[158:161], v[198:201], v[26:29]
	v_mfma_f32_16x16x32_bf16 v[10:13], v[158:161], v[206:209], v[10:13]
	v_mfma_f32_16x16x32_bf16 v[10:13], v[154:157], v[202:205], v[10:13]
	v_mfma_f32_16x16x32_bf16 v[54:57], v[162:165], v[178:181], v[54:57]
	v_mfma_f32_16x16x32_bf16 v[54:57], v[166:169], v[182:185], v[54:57]
	v_mfma_f32_16x16x32_bf16 v[38:41], v[166:169], v[190:193], v[38:41]
	v_mfma_f32_16x16x32_bf16 v[38:41], v[162:165], v[186:189], v[38:41]
	v_mfma_f32_16x16x32_bf16 v[22:25], v[162:165], v[194:197], v[22:25]
	v_mfma_f32_16x16x32_bf16 v[22:25], v[166:169], v[198:201], v[22:25]
	v_mfma_f32_16x16x32_bf16 v[6:9], v[166:169], v[206:209], v[6:9]
	v_mfma_f32_16x16x32_bf16 v[6:9], v[162:165], v[202:205], v[6:9]
	v_mfma_f32_16x16x32_bf16 v[50:53], v[170:173], v[178:181], v[50:53]
	v_mfma_f32_16x16x32_bf16 v[50:53], v[174:177], v[182:185], v[50:53]
	v_mfma_f32_16x16x32_bf16 v[34:37], v[174:177], v[190:193], v[34:37]
	v_mfma_f32_16x16x32_bf16 v[34:37], v[170:173], v[186:189], v[34:37]
	v_mfma_f32_16x16x32_bf16 v[18:21], v[170:173], v[194:197], v[18:21]
	v_mfma_f32_16x16x32_bf16 v[18:21], v[174:177], v[198:201], v[18:21]
	v_mfma_f32_16x16x32_bf16 v[2:5], v[174:177], v[206:209], v[2:5]
	v_mfma_f32_16x16x32_bf16 v[2:5], v[170:173], v[202:205], v[2:5]
	s_barrier
	v_add_u32_e32 v141, 0x18000, v139
	ds_read_b128 v[142:145], v141
	ds_read_b128 v[146:149], v141 offset:1024
	ds_read_b128 v[154:157], v141 offset:2048
	ds_read_b128 v[158:161], v141 offset:3072
	v_add_u32_e32 v141, 0x1c000, v139
	ds_read_b128 v[162:165], v141
	ds_read_b128 v[166:169], v141 offset:1024
	ds_read_b128 v[170:173], v141 offset:2048
	ds_read_b128 v[174:177], v141 offset:3072
	s_mov_b32 m0, s51
	ds_read_b128 v[178:181], v140 offset:32768
	ds_read_b128 v[182:185], v140 offset:33792
	buffer_load_dwordx4 v135, s[12:15], s84 offen lds
	s_mov_b32 m0, s63
	ds_read_b128 v[186:189], v140 offset:34816
	ds_read_b128 v[190:193], v140 offset:35840
	buffer_load_dwordx4 v137, s[12:15], s84 offen lds
	s_add_i32 s84, s84, 0x80000
	s_mov_b32 m0, s65
	ds_read_b128 v[194:197], v140 offset:36864
	ds_read_b128 v[198:201], v140 offset:37888
	buffer_load_dwordx4 v135, s[12:15], s84 offen lds
	s_mov_b32 m0, s66
	ds_read_b128 v[202:205], v140 offset:38912
	ds_read_b128 v[206:209], v140 offset:39936
	buffer_load_dwordx4 v137, s[12:15], s84 offen lds
	s_waitcnt vmcnt(8)
	s_waitcnt lgkmcnt(0)
	s_barrier
	s_waitcnt lgkmcnt(0)
	v_mfma_f32_16x16x32_bf16 v[126:129], v[142:145], v[178:181], v[126:129]
	v_mfma_f32_16x16x32_bf16 v[126:129], v[146:149], v[182:185], v[126:129]
	v_mfma_f32_16x16x32_bf16 v[110:113], v[146:149], v[190:193], v[110:113]
	v_mfma_f32_16x16x32_bf16 v[110:113], v[142:145], v[186:189], v[110:113]
	v_mfma_f32_16x16x32_bf16 v[94:97], v[142:145], v[194:197], v[94:97]
	v_mfma_f32_16x16x32_bf16 v[94:97], v[146:149], v[198:201], v[94:97]
	v_mfma_f32_16x16x32_bf16 v[78:81], v[146:149], v[206:209], v[78:81]
	v_mfma_f32_16x16x32_bf16 v[78:81], v[142:145], v[202:205], v[78:81]
	v_mfma_f32_16x16x32_bf16 v[122:125], v[154:157], v[178:181], v[122:125]
	v_mfma_f32_16x16x32_bf16 v[122:125], v[158:161], v[182:185], v[122:125]
	v_mfma_f32_16x16x32_bf16 v[106:109], v[158:161], v[190:193], v[106:109]
	v_mfma_f32_16x16x32_bf16 v[106:109], v[154:157], v[186:189], v[106:109]
	v_mfma_f32_16x16x32_bf16 v[90:93], v[154:157], v[194:197], v[90:93]
	v_mfma_f32_16x16x32_bf16 v[90:93], v[158:161], v[198:201], v[90:93]
	v_mfma_f32_16x16x32_bf16 v[74:77], v[158:161], v[206:209], v[74:77]
	v_mfma_f32_16x16x32_bf16 v[74:77], v[154:157], v[202:205], v[74:77]
	v_mfma_f32_16x16x32_bf16 v[118:121], v[162:165], v[178:181], v[118:121]
	v_mfma_f32_16x16x32_bf16 v[118:121], v[166:169], v[182:185], v[118:121]
	v_mfma_f32_16x16x32_bf16 v[102:105], v[166:169], v[190:193], v[102:105]
	v_mfma_f32_16x16x32_bf16 v[102:105], v[162:165], v[186:189], v[102:105]
	v_mfma_f32_16x16x32_bf16 v[86:89], v[162:165], v[194:197], v[86:89]
	v_mfma_f32_16x16x32_bf16 v[86:89], v[166:169], v[198:201], v[86:89]
	v_mfma_f32_16x16x32_bf16 v[70:73], v[166:169], v[206:209], v[70:73]
	v_mfma_f32_16x16x32_bf16 v[70:73], v[162:165], v[202:205], v[70:73]
	v_mfma_f32_16x16x32_bf16 v[114:117], v[170:173], v[178:181], v[114:117]
	v_mfma_f32_16x16x32_bf16 v[114:117], v[174:177], v[182:185], v[114:117]
	v_mfma_f32_16x16x32_bf16 v[98:101], v[174:177], v[190:193], v[98:101]
	v_mfma_f32_16x16x32_bf16 v[98:101], v[170:173], v[186:189], v[98:101]
	v_mfma_f32_16x16x32_bf16 v[82:85], v[170:173], v[194:197], v[82:85]
	v_mfma_f32_16x16x32_bf16 v[82:85], v[174:177], v[198:201], v[82:85]
	v_mfma_f32_16x16x32_bf16 v[66:69], v[174:177], v[206:209], v[66:69]
	v_mfma_f32_16x16x32_bf16 v[66:69], v[170:173], v[202:205], v[66:69]
	s_barrier
	s_mov_b32 m0, s67
	s_or_b32 s84, s83, 0x80
	ds_read_b128 v[178:181], v140 offset:49152
	ds_read_b128 v[182:185], v140 offset:50176
	buffer_load_dwordx4 v136, s[44:47], s84 offen lds
	s_mov_b32 m0, s68
	ds_read_b128 v[186:189], v140 offset:51200
	ds_read_b128 v[190:193], v140 offset:52224
	buffer_load_dwordx4 v138, s[44:47], s84 offen lds
	s_add_i32 s83, s83, 0x80080
	s_mov_b32 m0, s69
	ds_read_b128 v[194:197], v140 offset:53248
	ds_read_b128 v[198:201], v140 offset:54272
	buffer_load_dwordx4 v136, s[44:47], s83 offen lds
	s_mov_b32 m0, s70
	ds_read_b128 v[202:205], v140 offset:55296
	ds_read_b128 v[206:209], v140 offset:56320
	buffer_load_dwordx4 v138, s[44:47], s83 offen lds
	s_waitcnt vmcnt(6)
	s_waitcnt lgkmcnt(0)
	s_barrier
	s_waitcnt lgkmcnt(0)
	v_mfma_f32_16x16x32_bf16 v[62:65], v[142:145], v[178:181], v[62:65]
	v_mfma_f32_16x16x32_bf16 v[62:65], v[146:149], v[182:185], v[62:65]
	v_mfma_f32_16x16x32_bf16 v[46:49], v[146:149], v[190:193], v[46:49]
	v_mfma_f32_16x16x32_bf16 v[46:49], v[142:145], v[186:189], v[46:49]
	v_mfma_f32_16x16x32_bf16 v[30:33], v[142:145], v[194:197], v[30:33]
	v_mfma_f32_16x16x32_bf16 v[30:33], v[146:149], v[198:201], v[30:33]
	v_mfma_f32_16x16x32_bf16 v[14:17], v[146:149], v[206:209], v[14:17]
	v_mfma_f32_16x16x32_bf16 v[14:17], v[142:145], v[202:205], v[14:17]
	v_mfma_f32_16x16x32_bf16 v[58:61], v[154:157], v[178:181], v[58:61]
	v_mfma_f32_16x16x32_bf16 v[58:61], v[158:161], v[182:185], v[58:61]
	v_mfma_f32_16x16x32_bf16 v[42:45], v[158:161], v[190:193], v[42:45]
	v_mfma_f32_16x16x32_bf16 v[42:45], v[154:157], v[186:189], v[42:45]
	v_mfma_f32_16x16x32_bf16 v[26:29], v[154:157], v[194:197], v[26:29]
	v_mfma_f32_16x16x32_bf16 v[26:29], v[158:161], v[198:201], v[26:29]
	v_mfma_f32_16x16x32_bf16 v[10:13], v[158:161], v[206:209], v[10:13]
	v_mfma_f32_16x16x32_bf16 v[10:13], v[154:157], v[202:205], v[10:13]
	v_mfma_f32_16x16x32_bf16 v[54:57], v[162:165], v[178:181], v[54:57]
	v_mfma_f32_16x16x32_bf16 v[54:57], v[166:169], v[182:185], v[54:57]
	v_mfma_f32_16x16x32_bf16 v[38:41], v[166:169], v[190:193], v[38:41]
	v_mfma_f32_16x16x32_bf16 v[38:41], v[162:165], v[186:189], v[38:41]
	v_mfma_f32_16x16x32_bf16 v[22:25], v[162:165], v[194:197], v[22:25]
	v_mfma_f32_16x16x32_bf16 v[22:25], v[166:169], v[198:201], v[22:25]
	v_mfma_f32_16x16x32_bf16 v[6:9], v[166:169], v[206:209], v[6:9]
	v_mfma_f32_16x16x32_bf16 v[6:9], v[162:165], v[202:205], v[6:9]
	v_mfma_f32_16x16x32_bf16 v[50:53], v[170:173], v[178:181], v[50:53]
	v_mfma_f32_16x16x32_bf16 v[50:53], v[174:177], v[182:185], v[50:53]
	v_mfma_f32_16x16x32_bf16 v[34:37], v[174:177], v[190:193], v[34:37]
	v_mfma_f32_16x16x32_bf16 v[34:37], v[170:173], v[186:189], v[34:37]
	v_mfma_f32_16x16x32_bf16 v[18:21], v[170:173], v[194:197], v[18:21]
	v_mfma_f32_16x16x32_bf16 v[18:21], v[174:177], v[198:201], v[18:21]
	v_mfma_f32_16x16x32_bf16 v[2:5], v[174:177], v[206:209], v[2:5]
	v_mfma_f32_16x16x32_bf16 v[2:5], v[170:173], v[202:205], v[2:5]
	s_barrier
	s_add_i32 s81, s81, 2
	s_addk_i32 s82, 0x100
	s_cmp_gt_u32 s81, 29
	s_cbranch_scc0 .LBB0_605
	s_andn2_b64 vcc, exec, s[4:5]
	s_cbranch_vccnz .LBB0_597
	v_mov_b32_e32 v2, 0
	s_mov_b32 s42, s77
	s_mov_b32 s3, s78
	s_mov_b32 s59, s10
	s_mov_b32 s64, s9
	s_mov_b32 s75, s8
	v_mov_b32_e32 v3, v2
	v_mov_b32_e32 v4, v2
	v_mov_b32_e32 v5, v2
	v_mov_b32_e32 v6, v2
	v_mov_b32_e32 v7, v2
	v_mov_b32_e32 v8, v2
	v_mov_b32_e32 v9, v2
	v_mov_b32_e32 v18, v2
	v_mov_b32_e32 v19, v2
	v_mov_b32_e32 v20, v2
	v_mov_b32_e32 v21, v2
	v_mov_b32_e32 v22, v2
	v_mov_b32_e32 v23, v2
	v_mov_b32_e32 v24, v2
	v_mov_b32_e32 v25, v2
	v_mov_b32_e32 v34, v2
	v_mov_b32_e32 v35, v2
	v_mov_b32_e32 v36, v2
	v_mov_b32_e32 v37, v2
	v_mov_b32_e32 v38, v2
	v_mov_b32_e32 v39, v2
	v_mov_b32_e32 v40, v2
	v_mov_b32_e32 v41, v2
	v_mov_b32_e32 v50, v2
	v_mov_b32_e32 v51, v2
	v_mov_b32_e32 v52, v2
	v_mov_b32_e32 v53, v2
	v_mov_b32_e32 v54, v2
	v_mov_b32_e32 v55, v2
	v_mov_b32_e32 v56, v2
	v_mov_b32_e32 v57, v2
	v_mov_b32_e32 v10, v2
	v_mov_b32_e32 v11, v2
	v_mov_b32_e32 v12, v2
	v_mov_b32_e32 v13, v2
	v_mov_b32_e32 v14, v2
	v_mov_b32_e32 v15, v2
	v_mov_b32_e32 v16, v2
	v_mov_b32_e32 v17, v2
	v_mov_b32_e32 v26, v2
	v_mov_b32_e32 v27, v2
	v_mov_b32_e32 v28, v2
	v_mov_b32_e32 v29, v2
	v_mov_b32_e32 v30, v2
	v_mov_b32_e32 v31, v2
	v_mov_b32_e32 v32, v2
	v_mov_b32_e32 v33, v2
	v_mov_b32_e32 v42, v2
	v_mov_b32_e32 v43, v2
	v_mov_b32_e32 v44, v2
	v_mov_b32_e32 v45, v2
	v_mov_b32_e32 v46, v2
	v_mov_b32_e32 v47, v2
	v_mov_b32_e32 v48, v2
	v_mov_b32_e32 v49, v2
	v_mov_b32_e32 v58, v2
	v_mov_b32_e32 v59, v2
	v_mov_b32_e32 v60, v2
	v_mov_b32_e32 v61, v2
	v_mov_b32_e32 v62, v2
	v_mov_b32_e32 v63, v2
	v_mov_b32_e32 v64, v2
	v_mov_b32_e32 v65, v2
	v_mov_b32_e32 v66, v2
	v_mov_b32_e32 v67, v2
	v_mov_b32_e32 v68, v2
	v_mov_b32_e32 v69, v2
	v_mov_b32_e32 v70, v2
	v_mov_b32_e32 v71, v2
	v_mov_b32_e32 v72, v2
	v_mov_b32_e32 v73, v2
	v_mov_b32_e32 v82, v2
	v_mov_b32_e32 v83, v2
	v_mov_b32_e32 v84, v2
	v_mov_b32_e32 v85, v2
	v_mov_b32_e32 v86, v2
	v_mov_b32_e32 v87, v2
	v_mov_b32_e32 v88, v2
	v_mov_b32_e32 v89, v2
	v_mov_b32_e32 v98, v2
	v_mov_b32_e32 v99, v2
	v_mov_b32_e32 v100, v2
	v_mov_b32_e32 v101, v2
	v_mov_b32_e32 v102, v2
	v_mov_b32_e32 v103, v2
	v_mov_b32_e32 v104, v2
	v_mov_b32_e32 v105, v2
	v_mov_b32_e32 v114, v2
	v_mov_b32_e32 v115, v2
	v_mov_b32_e32 v116, v2
	v_mov_b32_e32 v117, v2
	v_mov_b32_e32 v118, v2
	v_mov_b32_e32 v119, v2
	v_mov_b32_e32 v120, v2
	v_mov_b32_e32 v121, v2
	v_mov_b32_e32 v74, v2
	v_mov_b32_e32 v75, v2
	v_mov_b32_e32 v76, v2
	v_mov_b32_e32 v77, v2
	v_mov_b32_e32 v78, v2
	v_mov_b32_e32 v79, v2
	v_mov_b32_e32 v80, v2
	v_mov_b32_e32 v81, v2
	v_mov_b32_e32 v90, v2
	v_mov_b32_e32 v91, v2
	v_mov_b32_e32 v92, v2
	v_mov_b32_e32 v93, v2
	v_mov_b32_e32 v94, v2
	v_mov_b32_e32 v95, v2
	v_mov_b32_e32 v96, v2
	v_mov_b32_e32 v97, v2
	v_mov_b32_e32 v106, v2
	v_mov_b32_e32 v107, v2
	v_mov_b32_e32 v108, v2
	v_mov_b32_e32 v109, v2
	v_mov_b32_e32 v110, v2
	v_mov_b32_e32 v111, v2
	v_mov_b32_e32 v112, v2
	v_mov_b32_e32 v113, v2
	v_mov_b32_e32 v122, v2
	v_mov_b32_e32 v123, v2
	v_mov_b32_e32 v124, v2
	v_mov_b32_e32 v125, v2
	v_mov_b32_e32 v126, v2
	v_mov_b32_e32 v127, v2
	v_mov_b32_e32 v128, v2
	v_mov_b32_e32 v129, v2
	s_branch .LBB0_597

.LBB0_822:
	ds_read_b128 v[66:69], v242
	ds_read_b128 v[70:73], v242 offset:1024
	ds_read_b128 v[74:77], v242 offset:2048
	ds_read_b128 v[78:81], v242 offset:3072
	ds_read_b128 v[82:85], v243
	ds_read_b128 v[86:89], v243 offset:1024
	ds_read_b128 v[90:93], v243 offset:2048
	ds_read_b128 v[94:97], v243 offset:3072
	s_add_i32 s43, s68, 0xfff80080
	s_cmp_eq_u32 s69, 28
	s_cselect_b32 s91, s11, s67
	s_cselect_b32 s92, s10, s43
	s_add_i32 s43, s68, 0xfff80000
	s_mov_b32 m0, s79
	ds_read_b128 v[98:101], v244
	ds_read_b128 v[102:105], v244 offset:1024
	buffer_load_dwordx4 v1, s[48:51], s43 offen lds
	s_mov_b32 m0, s80
	ds_read_b128 v[106:109], v244 offset:2048
	ds_read_b128 v[110:113], v244 offset:3072
	buffer_load_dwordx4 v236, s[48:51], s43 offen lds
	s_mov_b32 m0, s81
	ds_read_b128 v[114:117], v244 offset:4096
	ds_read_b128 v[118:121], v244 offset:5120
	buffer_load_dwordx4 v1, s[48:51], s68 offen lds
	s_mov_b32 m0, s82
	ds_read_b128 v[122:125], v244 offset:6144
	ds_read_b128 v[126:129], v244 offset:7168
	buffer_load_dwordx4 v236, s[48:51], s68 offen lds
	s_waitcnt vmcnt(8)
	s_waitcnt lgkmcnt(0)
	s_barrier
	s_waitcnt lgkmcnt(0)
	v_mfma_f32_16x16x32_bf16 v[190:193], v[66:69], v[98:101], v[190:193]
	v_mfma_f32_16x16x32_bf16 v[190:193], v[70:73], v[102:105], v[190:193]
	v_mfma_f32_16x16x32_bf16 v[174:177], v[70:73], v[110:113], v[174:177]
	v_mfma_f32_16x16x32_bf16 v[174:177], v[66:69], v[106:109], v[174:177]
	v_mfma_f32_16x16x32_bf16 v[170:173], v[66:69], v[114:117], v[170:173]
	v_mfma_f32_16x16x32_bf16 v[170:173], v[70:73], v[118:121], v[170:173]
	v_mfma_f32_16x16x32_bf16 v[158:161], v[70:73], v[126:129], v[158:161]
	v_mfma_f32_16x16x32_bf16 v[158:161], v[66:69], v[122:125], v[158:161]
	v_mfma_f32_16x16x32_bf16 v[186:189], v[74:77], v[98:101], v[186:189]
	v_mfma_f32_16x16x32_bf16 v[186:189], v[78:81], v[102:105], v[186:189]
	v_mfma_f32_16x16x32_bf16 v[166:169], v[78:81], v[110:113], v[166:169]
	v_mfma_f32_16x16x32_bf16 v[166:169], v[74:77], v[106:109], v[166:169]
	v_mfma_f32_16x16x32_bf16 v[162:165], v[74:77], v[114:117], v[162:165]
	v_mfma_f32_16x16x32_bf16 v[162:165], v[78:81], v[118:121], v[162:165]
	v_mfma_f32_16x16x32_bf16 v[154:157], v[78:81], v[126:129], v[154:157]
	v_mfma_f32_16x16x32_bf16 v[154:157], v[74:77], v[122:125], v[154:157]
	v_mfma_f32_16x16x32_bf16 v[182:185], v[82:85], v[98:101], v[182:185]
	v_mfma_f32_16x16x32_bf16 v[182:185], v[86:89], v[102:105], v[182:185]
	v_mfma_f32_16x16x32_bf16 v[98:101], v[90:93], v[98:101], v[178:181]
	v_mfma_f32_16x16x32_bf16 v[98:101], v[94:97], v[102:105], v[98:101]
	v_mfma_f32_16x16x32_bf16 v[102:105], v[82:85], v[106:109], v[150:153]
	v_mfma_f32_16x16x32_bf16 v[102:105], v[86:89], v[110:113], v[102:105]
	v_mfma_f32_16x16x32_bf16 v[106:109], v[90:93], v[106:109], v[142:145]
	v_mfma_f32_16x16x32_bf16 v[106:109], v[94:97], v[110:113], v[106:109]
	v_mfma_f32_16x16x32_bf16 v[110:113], v[82:85], v[114:117], v[146:149]
	v_mfma_f32_16x16x32_bf16 v[110:113], v[86:89], v[118:121], v[110:113]
	v_mfma_f32_16x16x32_bf16 v[114:117], v[90:93], v[114:117], v[138:141]
	v_mfma_f32_16x16x32_bf16 v[114:117], v[94:97], v[118:121], v[114:117]
	v_mfma_f32_16x16x32_bf16 v[118:121], v[82:85], v[122:125], v[134:137]
	v_mfma_f32_16x16x32_bf16 v[118:121], v[86:89], v[126:129], v[118:121]
	v_mfma_f32_16x16x32_bf16 v[122:125], v[90:93], v[122:125], v[130:133]
	v_mfma_f32_16x16x32_bf16 v[122:125], v[94:97], v[126:129], v[122:125]
	s_barrier
	s_mov_b32 m0, s29
	s_mov_b32 s43, s51
	ds_read_b128 v[126:129], v244 offset:16384
	ds_read_b128 v[130:133], v244 offset:17408
	buffer_load_dwordx4 v227, s[40:43], s91 offen lds
	s_mov_b32 m0, s35
	ds_read_b128 v[134:137], v244 offset:18432
	ds_read_b128 v[138:141], v244 offset:19456
	buffer_load_dwordx4 v237, s[40:43], s91 offen lds
	s_add_i32 s93, s91, 0x1600000
	s_mov_b32 m0, s63
	ds_read_b128 v[142:145], v244 offset:20480
	ds_read_b128 v[146:149], v244 offset:21504
	buffer_load_dwordx4 v227, s[40:43], s93 offen lds
	s_mov_b32 m0, s65
	ds_read_b128 v[150:153], v244 offset:22528
	ds_read_b128 v[178:181], v244 offset:23552
	buffer_load_dwordx4 v237, s[40:43], s93 offen lds
	s_waitcnt vmcnt(6)
	s_waitcnt lgkmcnt(0)
	s_barrier
	s_waitcnt lgkmcnt(0)
	v_mfma_f32_16x16x32_bf16 v[62:65], v[66:69], v[126:129], v[62:65]
	v_mfma_f32_16x16x32_bf16 v[62:65], v[70:73], v[130:133], v[62:65]
	v_mfma_f32_16x16x32_bf16 v[46:49], v[70:73], v[138:141], v[46:49]
	v_mfma_f32_16x16x32_bf16 v[46:49], v[66:69], v[134:137], v[46:49]
	v_mfma_f32_16x16x32_bf16 v[42:45], v[66:69], v[142:145], v[42:45]
	v_mfma_f32_16x16x32_bf16 v[42:45], v[70:73], v[146:149], v[42:45]
	v_mfma_f32_16x16x32_bf16 v[30:33], v[70:73], v[178:181], v[30:33]
	v_mfma_f32_16x16x32_bf16 v[30:33], v[66:69], v[150:153], v[30:33]
	v_mfma_f32_16x16x32_bf16 v[58:61], v[74:77], v[126:129], v[58:61]
	v_mfma_f32_16x16x32_bf16 v[58:61], v[78:81], v[130:133], v[58:61]
	v_mfma_f32_16x16x32_bf16 v[38:41], v[78:81], v[138:141], v[38:41]
	v_mfma_f32_16x16x32_bf16 v[38:41], v[74:77], v[134:137], v[38:41]
	v_mfma_f32_16x16x32_bf16 v[34:37], v[74:77], v[142:145], v[34:37]
	v_mfma_f32_16x16x32_bf16 v[34:37], v[78:81], v[146:149], v[34:37]
	v_mfma_f32_16x16x32_bf16 v[26:29], v[78:81], v[178:181], v[26:29]
	v_mfma_f32_16x16x32_bf16 v[26:29], v[74:77], v[150:153], v[26:29]
	v_mfma_f32_16x16x32_bf16 v[54:57], v[82:85], v[126:129], v[54:57]
	v_mfma_f32_16x16x32_bf16 v[54:57], v[86:89], v[130:133], v[54:57]
	v_mfma_f32_16x16x32_bf16 v[22:25], v[86:89], v[138:141], v[22:25]
	v_mfma_f32_16x16x32_bf16 v[22:25], v[82:85], v[134:137], v[22:25]
	v_mfma_f32_16x16x32_bf16 v[18:21], v[82:85], v[142:145], v[18:21]
	v_mfma_f32_16x16x32_bf16 v[18:21], v[86:89], v[146:149], v[18:21]
	v_mfma_f32_16x16x32_bf16 v[6:9], v[86:89], v[178:181], v[6:9]
	v_mfma_f32_16x16x32_bf16 v[6:9], v[82:85], v[150:153], v[6:9]
	v_mfma_f32_16x16x32_bf16 v[50:53], v[90:93], v[126:129], v[50:53]
	v_mfma_f32_16x16x32_bf16 v[50:53], v[94:97], v[130:133], v[50:53]
	v_mfma_f32_16x16x32_bf16 v[14:17], v[94:97], v[138:141], v[14:17]
	v_mfma_f32_16x16x32_bf16 v[14:17], v[90:93], v[134:137], v[14:17]
	v_mfma_f32_16x16x32_bf16 v[10:13], v[90:93], v[142:145], v[10:13]
	v_mfma_f32_16x16x32_bf16 v[10:13], v[94:97], v[146:149], v[10:13]
	v_mfma_f32_16x16x32_bf16 v[2:5], v[94:97], v[178:181], v[2:5]
	v_mfma_f32_16x16x32_bf16 v[2:5], v[90:93], v[150:153], v[2:5]
	s_barrier
	ds_read_b128 v[66:69], v245
	ds_read_b128 v[70:73], v245 offset:1024
	ds_read_b128 v[74:77], v245 offset:2048
	ds_read_b128 v[78:81], v245 offset:3072
	ds_read_b128 v[82:85], v246
	ds_read_b128 v[86:89], v246 offset:1024
	ds_read_b128 v[90:93], v246 offset:2048
	ds_read_b128 v[94:97], v246 offset:3072
	s_mov_b32 m0, s3
	ds_read_b128 v[126:129], v244 offset:32768
	ds_read_b128 v[130:133], v244 offset:33792
	buffer_load_dwordx4 v1, s[48:51], s92 offen lds
	s_mov_b32 m0, s70
	ds_read_b128 v[134:137], v244 offset:34816
	ds_read_b128 v[138:141], v244 offset:35840
	buffer_load_dwordx4 v236, s[48:51], s92 offen lds
	s_add_i32 s92, s92, 0x80000
	s_mov_b32 m0, s71
	ds_read_b128 v[194:197], v244 offset:36864
	ds_read_b128 v[198:201], v244 offset:37888
	buffer_load_dwordx4 v1, s[48:51], s92 offen lds
	s_mov_b32 m0, s72
	ds_read_b128 v[202:205], v244 offset:38912
	ds_read_b128 v[206:209], v244 offset:39936
	buffer_load_dwordx4 v236, s[48:51], s92 offen lds
	s_waitcnt vmcnt(8)
	s_waitcnt lgkmcnt(0)
	s_barrier
	s_waitcnt lgkmcnt(0)
	v_mfma_f32_16x16x32_bf16 v[142:145], v[66:69], v[126:129], v[190:193]
	v_mfma_f32_16x16x32_bf16 v[190:193], v[70:73], v[130:133], v[142:145]
	v_mfma_f32_16x16x32_bf16 v[142:145], v[74:77], v[126:129], v[186:189]
	v_mfma_f32_16x16x32_bf16 v[186:189], v[78:81], v[130:133], v[142:145]
	v_mfma_f32_16x16x32_bf16 v[142:145], v[66:69], v[134:137], v[174:177]
	v_mfma_f32_16x16x32_bf16 v[174:177], v[70:73], v[138:141], v[142:145]
	v_mfma_f32_16x16x32_bf16 v[142:145], v[74:77], v[134:137], v[166:169]
	v_mfma_f32_16x16x32_bf16 v[166:169], v[78:81], v[138:141], v[142:145]
	v_mfma_f32_16x16x32_bf16 v[142:145], v[66:69], v[194:197], v[170:173]
	v_mfma_f32_16x16x32_bf16 v[170:173], v[70:73], v[198:201], v[142:145]
	v_mfma_f32_16x16x32_bf16 v[142:145], v[74:77], v[194:197], v[162:165]
	v_mfma_f32_16x16x32_bf16 v[162:165], v[78:81], v[198:201], v[142:145]
	v_mfma_f32_16x16x32_bf16 v[142:145], v[66:69], v[202:205], v[158:161]
	v_mfma_f32_16x16x32_bf16 v[158:161], v[70:73], v[206:209], v[142:145]
	v_mfma_f32_16x16x32_bf16 v[142:145], v[74:77], v[202:205], v[154:157]
	v_mfma_f32_16x16x32_bf16 v[154:157], v[78:81], v[206:209], v[142:145]
	v_mfma_f32_16x16x32_bf16 v[98:101], v[90:93], v[126:129], v[98:101]
	v_mfma_f32_16x16x32_bf16 v[178:181], v[94:97], v[130:133], v[98:101]
	v_mfma_f32_16x16x32_bf16 v[98:101], v[82:85], v[134:137], v[102:105]
	v_mfma_f32_16x16x32_bf16 v[150:153], v[86:89], v[138:141], v[98:101]
	v_mfma_f32_16x16x32_bf16 v[98:101], v[90:93], v[134:137], v[106:109]
	v_mfma_f32_16x16x32_bf16 v[142:145], v[82:85], v[126:129], v[182:185]
	v_mfma_f32_16x16x32_bf16 v[182:185], v[86:89], v[130:133], v[142:145]
	v_mfma_f32_16x16x32_bf16 v[142:145], v[94:97], v[138:141], v[98:101]
	v_mfma_f32_16x16x32_bf16 v[98:101], v[82:85], v[194:197], v[110:113]
	v_mfma_f32_16x16x32_bf16 v[146:149], v[86:89], v[198:201], v[98:101]
	v_mfma_f32_16x16x32_bf16 v[98:101], v[90:93], v[194:197], v[114:117]
	v_mfma_f32_16x16x32_bf16 v[138:141], v[94:97], v[198:201], v[98:101]
	v_mfma_f32_16x16x32_bf16 v[98:101], v[82:85], v[202:205], v[118:121]
	v_mfma_f32_16x16x32_bf16 v[134:137], v[86:89], v[206:209], v[98:101]
	v_mfma_f32_16x16x32_bf16 v[98:101], v[90:93], v[202:205], v[122:125]
	v_mfma_f32_16x16x32_bf16 v[130:133], v[94:97], v[206:209], v[98:101]
	s_barrier
	s_mov_b32 m0, s74
	s_or_b32 s92, s91, 0x80
	s_nop 2
	ds_read_b128 v[98:101], v244 offset:49152
	ds_read_b128 v[102:105], v244 offset:50176
	buffer_load_dwordx4 v227, s[40:43], s92 offen lds
	s_mov_b32 m0, s75
	ds_read_b128 v[106:109], v244 offset:51200
	ds_read_b128 v[110:113], v244 offset:52224
	buffer_load_dwordx4 v237, s[40:43], s92 offen lds
	s_add_i32 s91, s91, 0x1600080
	s_mov_b32 m0, s77
	ds_read_b128 v[114:117], v244 offset:53248
	ds_read_b128 v[118:121], v244 offset:54272
	buffer_load_dwordx4 v227, s[40:43], s91 offen lds
	s_mov_b32 m0, s78
	ds_read_b128 v[122:125], v244 offset:55296
	ds_read_b128 v[126:129], v244 offset:56320
	buffer_load_dwordx4 v237, s[40:43], s91 offen lds
	s_waitcnt vmcnt(6)
	s_waitcnt lgkmcnt(0)
	s_barrier
	s_waitcnt lgkmcnt(0)
	v_mfma_f32_16x16x32_bf16 v[62:65], v[66:69], v[98:101], v[62:65]
	v_mfma_f32_16x16x32_bf16 v[62:65], v[70:73], v[102:105], v[62:65]
	v_mfma_f32_16x16x32_bf16 v[46:49], v[70:73], v[110:113], v[46:49]
	v_mfma_f32_16x16x32_bf16 v[46:49], v[66:69], v[106:109], v[46:49]
	v_mfma_f32_16x16x32_bf16 v[42:45], v[66:69], v[114:117], v[42:45]
	v_mfma_f32_16x16x32_bf16 v[42:45], v[70:73], v[118:121], v[42:45]
	v_mfma_f32_16x16x32_bf16 v[30:33], v[70:73], v[126:129], v[30:33]
	v_mfma_f32_16x16x32_bf16 v[30:33], v[66:69], v[122:125], v[30:33]
	v_mfma_f32_16x16x32_bf16 v[58:61], v[74:77], v[98:101], v[58:61]
	v_mfma_f32_16x16x32_bf16 v[58:61], v[78:81], v[102:105], v[58:61]
	v_mfma_f32_16x16x32_bf16 v[38:41], v[78:81], v[110:113], v[38:41]
	v_mfma_f32_16x16x32_bf16 v[38:41], v[74:77], v[106:109], v[38:41]
	v_mfma_f32_16x16x32_bf16 v[34:37], v[74:77], v[114:117], v[34:37]
	v_mfma_f32_16x16x32_bf16 v[34:37], v[78:81], v[118:121], v[34:37]
	v_mfma_f32_16x16x32_bf16 v[26:29], v[78:81], v[126:129], v[26:29]
	v_mfma_f32_16x16x32_bf16 v[26:29], v[74:77], v[122:125], v[26:29]
	v_mfma_f32_16x16x32_bf16 v[54:57], v[82:85], v[98:101], v[54:57]
	v_mfma_f32_16x16x32_bf16 v[54:57], v[86:89], v[102:105], v[54:57]
	v_mfma_f32_16x16x32_bf16 v[22:25], v[86:89], v[110:113], v[22:25]
	v_mfma_f32_16x16x32_bf16 v[22:25], v[82:85], v[106:109], v[22:25]
	v_mfma_f32_16x16x32_bf16 v[18:21], v[82:85], v[114:117], v[18:21]
	v_mfma_f32_16x16x32_bf16 v[18:21], v[86:89], v[118:121], v[18:21]
	v_mfma_f32_16x16x32_bf16 v[6:9], v[86:89], v[126:129], v[6:9]
	v_mfma_f32_16x16x32_bf16 v[6:9], v[82:85], v[122:125], v[6:9]
	v_mfma_f32_16x16x32_bf16 v[50:53], v[90:93], v[98:101], v[50:53]
	v_mfma_f32_16x16x32_bf16 v[50:53], v[94:97], v[102:105], v[50:53]
	v_mfma_f32_16x16x32_bf16 v[14:17], v[94:97], v[110:113], v[14:17]
	v_mfma_f32_16x16x32_bf16 v[14:17], v[90:93], v[106:109], v[14:17]
	v_mfma_f32_16x16x32_bf16 v[10:13], v[90:93], v[114:117], v[10:13]
	v_mfma_f32_16x16x32_bf16 v[10:13], v[94:97], v[118:121], v[10:13]
	v_mfma_f32_16x16x32_bf16 v[2:5], v[94:97], v[126:129], v[2:5]
	v_mfma_f32_16x16x32_bf16 v[2:5], v[90:93], v[122:125], v[2:5]
	s_barrier
	s_add_i32 s69, s69, 2
	s_addk_i32 s67, 0x100
	s_addk_i32 s68, 0x100
	s_cmp_gt_u32 s69, 29
	s_cbranch_scc0 .LBB0_822
	s_and_b64 vcc, exec, s[38:39]
	s_cbranch_vccz .LBB0_825
	s_barrier

.LBB0_1003:
	v_add_u32_e32 v130, 0x10000, v155
	ds_read_b128 v[132:135], v130
	ds_read_b128 v[144:147], v130 offset:1024
	ds_read_b128 v[158:161], v130 offset:2048
	ds_read_b128 v[162:165], v130 offset:3072
	v_add_u32_e32 v130, 0x14000, v155
	s_lshl_b32 s39, s92, 7
	ds_read_b128 v[166:169], v130
	ds_read_b128 v[170:173], v130 offset:1024
	ds_read_b128 v[174:177], v130 offset:2048
	ds_read_b128 v[178:181], v130 offset:3072
	s_add_i32 s93, s61, s39
	s_addk_i32 s39, 0x100
	s_add_i32 s94, s93, 0x80
	s_add_i32 s95, s39, s61
	s_and_b64 s[50:51], s[48:49], exec
	s_cselect_b32 s50, s87, s95
	s_add_i32 s39, s39, s63
	s_and_b64 s[48:49], s[48:49], exec
	s_cselect_b32 s48, s88, s39
	s_or_b32 s49, s48, 0x80
	s_mov_b32 m0, s77
	ds_read_b128 v[182:185], v156
	ds_read_b128 v[186:189], v156 offset:1024
	buffer_load_dwordx4 v151, s[28:31], s94 offen lds
	s_mov_b32 m0, s78
	ds_read_b128 v[190:193], v156 offset:2048
	ds_read_b128 v[194:197], v156 offset:3072
	buffer_load_dwordx4 v153, s[28:31], s94 offen lds
	s_add_i32 s93, s93, 0x160080
	s_mov_b32 m0, s79
	ds_read_b128 v[198:201], v156 offset:4096
	ds_read_b128 v[202:205], v156 offset:5120
	buffer_load_dwordx4 v151, s[28:31], s93 offen lds
	s_mov_b32 m0, s80
	ds_read_b128 v[206:209], v156 offset:6144
	ds_read_b128 v[210:213], v156 offset:7168
	buffer_load_dwordx4 v153, s[28:31], s93 offen lds
	s_waitcnt vmcnt(8)
	s_waitcnt lgkmcnt(0)
	s_barrier
	s_waitcnt lgkmcnt(0)
	v_mfma_f32_16x16x32_bf16 v[126:129], v[132:135], v[182:185], v[126:129]
	v_mfma_f32_16x16x32_bf16 v[126:129], v[144:147], v[186:189], v[126:129]
	v_mfma_f32_16x16x32_bf16 v[110:113], v[144:147], v[194:197], v[110:113]
	v_mfma_f32_16x16x32_bf16 v[110:113], v[132:135], v[190:193], v[110:113]
	v_mfma_f32_16x16x32_bf16 v[94:97], v[132:135], v[198:201], v[94:97]
	v_mfma_f32_16x16x32_bf16 v[94:97], v[144:147], v[202:205], v[94:97]
	v_mfma_f32_16x16x32_bf16 v[78:81], v[144:147], v[210:213], v[78:81]
	v_mfma_f32_16x16x32_bf16 v[78:81], v[132:135], v[206:209], v[78:81]
	v_mfma_f32_16x16x32_bf16 v[122:125], v[158:161], v[182:185], v[122:125]
	v_mfma_f32_16x16x32_bf16 v[122:125], v[162:165], v[186:189], v[122:125]
	v_mfma_f32_16x16x32_bf16 v[106:109], v[162:165], v[194:197], v[106:109]
	v_mfma_f32_16x16x32_bf16 v[106:109], v[158:161], v[190:193], v[106:109]
	v_mfma_f32_16x16x32_bf16 v[90:93], v[158:161], v[198:201], v[90:93]
	v_mfma_f32_16x16x32_bf16 v[90:93], v[162:165], v[202:205], v[90:93]
	v_mfma_f32_16x16x32_bf16 v[74:77], v[162:165], v[210:213], v[74:77]
	v_mfma_f32_16x16x32_bf16 v[74:77], v[158:161], v[206:209], v[74:77]
	v_mfma_f32_16x16x32_bf16 v[118:121], v[166:169], v[182:185], v[118:121]
	v_mfma_f32_16x16x32_bf16 v[118:121], v[170:173], v[186:189], v[118:121]
	v_mfma_f32_16x16x32_bf16 v[102:105], v[170:173], v[194:197], v[102:105]
	v_mfma_f32_16x16x32_bf16 v[102:105], v[166:169], v[190:193], v[102:105]
	v_mfma_f32_16x16x32_bf16 v[86:89], v[166:169], v[198:201], v[86:89]
	v_mfma_f32_16x16x32_bf16 v[86:89], v[170:173], v[202:205], v[86:89]
	v_mfma_f32_16x16x32_bf16 v[70:73], v[170:173], v[210:213], v[70:73]
	v_mfma_f32_16x16x32_bf16 v[70:73], v[166:169], v[206:209], v[70:73]
	v_mfma_f32_16x16x32_bf16 v[114:117], v[174:177], v[182:185], v[114:117]
	v_mfma_f32_16x16x32_bf16 v[114:117], v[178:181], v[186:189], v[114:117]
	v_mfma_f32_16x16x32_bf16 v[98:101], v[178:181], v[194:197], v[98:101]
	v_mfma_f32_16x16x32_bf16 v[98:101], v[174:177], v[190:193], v[98:101]
	v_mfma_f32_16x16x32_bf16 v[82:85], v[174:177], v[198:201], v[82:85]
	v_mfma_f32_16x16x32_bf16 v[82:85], v[178:181], v[202:205], v[82:85]
	v_mfma_f32_16x16x32_bf16 v[66:69], v[178:181], v[210:213], v[66:69]
	v_mfma_f32_16x16x32_bf16 v[66:69], v[174:177], v[206:209], v[66:69]
	s_barrier
	s_mov_b32 m0, s64
	s_mov_b32 s39, s31
	ds_read_b128 v[182:185], v156 offset:16384
	ds_read_b128 v[186:189], v156 offset:17408
	buffer_load_dwordx4 v152, s[36:39], s48 offen lds
	s_mov_b32 m0, s65
	ds_read_b128 v[190:193], v156 offset:18432
	ds_read_b128 v[194:197], v156 offset:19456
	buffer_load_dwordx4 v154, s[36:39], s48 offen lds
	s_add_i32 s51, s48, 0x160000
	s_mov_b32 m0, s66
	ds_read_b128 v[198:201], v156 offset:20480
	ds_read_b128 v[202:205], v156 offset:21504
	buffer_load_dwordx4 v152, s[36:39], s51 offen lds
	s_mov_b32 m0, s67
	ds_read_b128 v[206:209], v156 offset:22528
	ds_read_b128 v[210:213], v156 offset:23552
	buffer_load_dwordx4 v154, s[36:39], s51 offen lds
	s_waitcnt vmcnt(6)
	s_waitcnt lgkmcnt(0)
	s_barrier
	s_waitcnt lgkmcnt(0)
	v_mfma_f32_16x16x32_bf16 v[62:65], v[132:135], v[182:185], v[62:65]
	v_mfma_f32_16x16x32_bf16 v[62:65], v[144:147], v[186:189], v[62:65]
	v_mfma_f32_16x16x32_bf16 v[46:49], v[144:147], v[194:197], v[46:49]
	v_mfma_f32_16x16x32_bf16 v[46:49], v[132:135], v[190:193], v[46:49]
	v_mfma_f32_16x16x32_bf16 v[30:33], v[132:135], v[198:201], v[30:33]
	v_mfma_f32_16x16x32_bf16 v[30:33], v[144:147], v[202:205], v[30:33]
	v_mfma_f32_16x16x32_bf16 v[14:17], v[144:147], v[210:213], v[14:17]
	v_mfma_f32_16x16x32_bf16 v[14:17], v[132:135], v[206:209], v[14:17]
	v_mfma_f32_16x16x32_bf16 v[58:61], v[158:161], v[182:185], v[58:61]
	v_mfma_f32_16x16x32_bf16 v[58:61], v[162:165], v[186:189], v[58:61]
	v_mfma_f32_16x16x32_bf16 v[42:45], v[162:165], v[194:197], v[42:45]
	v_mfma_f32_16x16x32_bf16 v[42:45], v[158:161], v[190:193], v[42:45]
	v_mfma_f32_16x16x32_bf16 v[26:29], v[158:161], v[198:201], v[26:29]
	v_mfma_f32_16x16x32_bf16 v[26:29], v[162:165], v[202:205], v[26:29]
	v_mfma_f32_16x16x32_bf16 v[10:13], v[162:165], v[210:213], v[10:13]
	v_mfma_f32_16x16x32_bf16 v[10:13], v[158:161], v[206:209], v[10:13]
	v_mfma_f32_16x16x32_bf16 v[54:57], v[166:169], v[182:185], v[54:57]
	v_mfma_f32_16x16x32_bf16 v[54:57], v[170:173], v[186:189], v[54:57]
	v_mfma_f32_16x16x32_bf16 v[38:41], v[170:173], v[194:197], v[38:41]
	v_mfma_f32_16x16x32_bf16 v[38:41], v[166:169], v[190:193], v[38:41]
	v_mfma_f32_16x16x32_bf16 v[22:25], v[166:169], v[198:201], v[22:25]
	v_mfma_f32_16x16x32_bf16 v[22:25], v[170:173], v[202:205], v[22:25]
	v_mfma_f32_16x16x32_bf16 v[6:9], v[170:173], v[210:213], v[6:9]
	v_mfma_f32_16x16x32_bf16 v[6:9], v[166:169], v[206:209], v[6:9]
	v_mfma_f32_16x16x32_bf16 v[50:53], v[174:177], v[182:185], v[50:53]
	v_mfma_f32_16x16x32_bf16 v[50:53], v[178:181], v[186:189], v[50:53]
	v_mfma_f32_16x16x32_bf16 v[34:37], v[178:181], v[194:197], v[34:37]
	v_mfma_f32_16x16x32_bf16 v[34:37], v[174:177], v[190:193], v[34:37]
	v_mfma_f32_16x16x32_bf16 v[18:21], v[174:177], v[198:201], v[18:21]
	v_mfma_f32_16x16x32_bf16 v[18:21], v[178:181], v[202:205], v[18:21]
	v_mfma_f32_16x16x32_bf16 v[2:5], v[178:181], v[210:213], v[2:5]
	v_mfma_f32_16x16x32_bf16 v[2:5], v[174:177], v[206:209], v[2:5]
	s_barrier
	v_add_u32_e32 v130, 0x18000, v155
	ds_read_b128 v[132:135], v130
	ds_read_b128 v[144:147], v130 offset:1024
	ds_read_b128 v[158:161], v130 offset:2048
	ds_read_b128 v[162:165], v130 offset:3072
	v_add_u32_e32 v130, 0x1c000, v155
	ds_read_b128 v[166:169], v130
	ds_read_b128 v[170:173], v130 offset:1024
	ds_read_b128 v[174:177], v130 offset:2048
	ds_read_b128 v[178:181], v130 offset:3072
	s_mov_b32 m0, s62
	ds_read_b128 v[182:185], v156 offset:32768
	ds_read_b128 v[186:189], v156 offset:33792
	buffer_load_dwordx4 v151, s[28:31], s50 offen lds
	s_mov_b32 m0, s68
	ds_read_b128 v[190:193], v156 offset:34816
	ds_read_b128 v[194:197], v156 offset:35840
	buffer_load_dwordx4 v153, s[28:31], s50 offen lds
	s_add_i32 s50, s50, 0x160000
	s_mov_b32 m0, s69
	ds_read_b128 v[198:201], v156 offset:36864
	ds_read_b128 v[202:205], v156 offset:37888
	buffer_load_dwordx4 v151, s[28:31], s50 offen lds
	s_mov_b32 m0, s70
	ds_read_b128 v[206:209], v156 offset:38912
	ds_read_b128 v[210:213], v156 offset:39936
	buffer_load_dwordx4 v153, s[28:31], s50 offen lds
	s_waitcnt vmcnt(8)
	s_waitcnt lgkmcnt(0)
	s_barrier
	s_waitcnt lgkmcnt(0)
	v_mfma_f32_16x16x32_bf16 v[126:129], v[132:135], v[182:185], v[126:129]
	v_mfma_f32_16x16x32_bf16 v[126:129], v[144:147], v[186:189], v[126:129]
	v_mfma_f32_16x16x32_bf16 v[110:113], v[144:147], v[194:197], v[110:113]
	v_mfma_f32_16x16x32_bf16 v[110:113], v[132:135], v[190:193], v[110:113]
	v_mfma_f32_16x16x32_bf16 v[94:97], v[132:135], v[198:201], v[94:97]
	v_mfma_f32_16x16x32_bf16 v[94:97], v[144:147], v[202:205], v[94:97]
	v_mfma_f32_16x16x32_bf16 v[78:81], v[144:147], v[210:213], v[78:81]
	v_mfma_f32_16x16x32_bf16 v[78:81], v[132:135], v[206:209], v[78:81]
	v_mfma_f32_16x16x32_bf16 v[122:125], v[158:161], v[182:185], v[122:125]
	v_mfma_f32_16x16x32_bf16 v[122:125], v[162:165], v[186:189], v[122:125]
	v_mfma_f32_16x16x32_bf16 v[106:109], v[162:165], v[194:197], v[106:109]
	v_mfma_f32_16x16x32_bf16 v[106:109], v[158:161], v[190:193], v[106:109]
	v_mfma_f32_16x16x32_bf16 v[90:93], v[158:161], v[198:201], v[90:93]
	v_mfma_f32_16x16x32_bf16 v[90:93], v[162:165], v[202:205], v[90:93]
	v_mfma_f32_16x16x32_bf16 v[74:77], v[162:165], v[210:213], v[74:77]
	v_mfma_f32_16x16x32_bf16 v[74:77], v[158:161], v[206:209], v[74:77]
	v_mfma_f32_16x16x32_bf16 v[118:121], v[166:169], v[182:185], v[118:121]
	v_mfma_f32_16x16x32_bf16 v[118:121], v[170:173], v[186:189], v[118:121]
	v_mfma_f32_16x16x32_bf16 v[102:105], v[170:173], v[194:197], v[102:105]
	v_mfma_f32_16x16x32_bf16 v[102:105], v[166:169], v[190:193], v[102:105]
	v_mfma_f32_16x16x32_bf16 v[86:89], v[166:169], v[198:201], v[86:89]
	v_mfma_f32_16x16x32_bf16 v[86:89], v[170:173], v[202:205], v[86:89]
	v_mfma_f32_16x16x32_bf16 v[70:73], v[170:173], v[210:213], v[70:73]
	v_mfma_f32_16x16x32_bf16 v[70:73], v[166:169], v[206:209], v[70:73]
	v_mfma_f32_16x16x32_bf16 v[114:117], v[174:177], v[182:185], v[114:117]
	v_mfma_f32_16x16x32_bf16 v[114:117], v[178:181], v[186:189], v[114:117]
	v_mfma_f32_16x16x32_bf16 v[98:101], v[178:181], v[194:197], v[98:101]
	v_mfma_f32_16x16x32_bf16 v[98:101], v[174:177], v[190:193], v[98:101]
	v_mfma_f32_16x16x32_bf16 v[82:85], v[174:177], v[198:201], v[82:85]
	v_mfma_f32_16x16x32_bf16 v[82:85], v[178:181], v[202:205], v[82:85]
	v_mfma_f32_16x16x32_bf16 v[66:69], v[178:181], v[210:213], v[66:69]
	v_mfma_f32_16x16x32_bf16 v[66:69], v[174:177], v[206:209], v[66:69]
	s_barrier
	s_mov_b32 m0, s72
	ds_read_b128 v[182:185], v156 offset:49152
	ds_read_b128 v[186:189], v156 offset:50176
	buffer_load_dwordx4 v152, s[36:39], s49 offen lds
	s_mov_b32 m0, s73
	ds_read_b128 v[190:193], v156 offset:51200
	ds_read_b128 v[194:197], v156 offset:52224
	buffer_load_dwordx4 v154, s[36:39], s49 offen lds
	s_add_i32 s48, s48, 0x160080
	s_mov_b32 m0, s74
	ds_read_b128 v[198:201], v156 offset:53248
	ds_read_b128 v[202:205], v156 offset:54272
	buffer_load_dwordx4 v152, s[36:39], s48 offen lds
	s_mov_b32 m0, s75
	ds_read_b128 v[206:209], v156 offset:55296
	ds_read_b128 v[210:213], v156 offset:56320
	buffer_load_dwordx4 v154, s[36:39], s48 offen lds
	s_waitcnt vmcnt(6)
	s_waitcnt lgkmcnt(0)
	s_barrier
	s_waitcnt lgkmcnt(0)
	v_mfma_f32_16x16x32_bf16 v[62:65], v[132:135], v[182:185], v[62:65]
	v_mfma_f32_16x16x32_bf16 v[62:65], v[144:147], v[186:189], v[62:65]
	v_mfma_f32_16x16x32_bf16 v[46:49], v[144:147], v[194:197], v[46:49]
	v_mfma_f32_16x16x32_bf16 v[46:49], v[132:135], v[190:193], v[46:49]
	v_mfma_f32_16x16x32_bf16 v[30:33], v[132:135], v[198:201], v[30:33]
	v_mfma_f32_16x16x32_bf16 v[30:33], v[144:147], v[202:205], v[30:33]
	v_mfma_f32_16x16x32_bf16 v[14:17], v[144:147], v[210:213], v[14:17]
	v_mfma_f32_16x16x32_bf16 v[14:17], v[132:135], v[206:209], v[14:17]
	v_mfma_f32_16x16x32_bf16 v[58:61], v[158:161], v[182:185], v[58:61]
	v_mfma_f32_16x16x32_bf16 v[58:61], v[162:165], v[186:189], v[58:61]
	v_mfma_f32_16x16x32_bf16 v[42:45], v[162:165], v[194:197], v[42:45]
	v_mfma_f32_16x16x32_bf16 v[42:45], v[158:161], v[190:193], v[42:45]
	v_mfma_f32_16x16x32_bf16 v[26:29], v[158:161], v[198:201], v[26:29]
	v_mfma_f32_16x16x32_bf16 v[26:29], v[162:165], v[202:205], v[26:29]
	v_mfma_f32_16x16x32_bf16 v[10:13], v[162:165], v[210:213], v[10:13]
	v_mfma_f32_16x16x32_bf16 v[10:13], v[158:161], v[206:209], v[10:13]
	v_mfma_f32_16x16x32_bf16 v[54:57], v[166:169], v[182:185], v[54:57]
	v_mfma_f32_16x16x32_bf16 v[54:57], v[170:173], v[186:189], v[54:57]
	v_mfma_f32_16x16x32_bf16 v[38:41], v[170:173], v[194:197], v[38:41]
	v_mfma_f32_16x16x32_bf16 v[38:41], v[166:169], v[190:193], v[38:41]
	v_mfma_f32_16x16x32_bf16 v[22:25], v[166:169], v[198:201], v[22:25]
	v_mfma_f32_16x16x32_bf16 v[22:25], v[170:173], v[202:205], v[22:25]
	v_mfma_f32_16x16x32_bf16 v[6:9], v[170:173], v[210:213], v[6:9]
	v_mfma_f32_16x16x32_bf16 v[6:9], v[166:169], v[206:209], v[6:9]
	v_mfma_f32_16x16x32_bf16 v[50:53], v[174:177], v[182:185], v[50:53]
	v_mfma_f32_16x16x32_bf16 v[50:53], v[178:181], v[186:189], v[50:53]
	v_mfma_f32_16x16x32_bf16 v[34:37], v[178:181], v[194:197], v[34:37]
	v_mfma_f32_16x16x32_bf16 v[34:37], v[174:177], v[190:193], v[34:37]
	v_mfma_f32_16x16x32_bf16 v[18:21], v[174:177], v[198:201], v[18:21]
	v_mfma_f32_16x16x32_bf16 v[18:21], v[178:181], v[202:205], v[18:21]
	v_mfma_f32_16x16x32_bf16 v[2:5], v[178:181], v[210:213], v[2:5]
	v_mfma_f32_16x16x32_bf16 v[2:5], v[174:177], v[206:209], v[2:5]
	s_barrier
	s_add_i32 s39, s92, 2
	s_cmpk_gt_u32 s92, 0x55
	s_cbranch_scc1 .LBB0_1005
	s_mov_b32 s92, s39
	s_branch .LBB0_999
